# GEMM K-loops: phase-5 B0 fragment ds_reads issued under phase 4's read-free MFMA burst (address calc hoisted into phase 4's load segment)
# speedup vs baseline: 1.0295x; 1.0010x over previous
; #define PG8_STAGE(bufoff, gbase, v0, v1) do { \
;         __builtin_amdgcn_global_load_lds((const unsigned*)((const char*)(gbase) + (v0)), (LAS unsigned*)(lds + (bufoff) + ldsw), 16, 0, 0); \
;         __builtin_amdgcn_global_load_lds((const unsigned*)((const char*)(gbase) + (v1)), (LAS unsigned*)(lds + (bufoff) + ldsw + 8192), 16, 0, 0); } while (0)
; #define PG8_LDA(dst, b, h) do { _Pragma("unroll") for (int m = 0; m < 4; ++m) _Pragma("unroll") for (int k = 0; k < 2; ++k) dst[m][k] = *(const LAS bf16x8*)(lds + PG8_SA(b, h) + aoff + m * 2048 + k * 1024); } while (0)
; #define PG8_LDB(dst, b, h) do { _Pragma("unroll") for (int n = 0; n < 2; ++n) _Pragma("unroll") for (int k = 0; k < 2; ++k) dst[n][k] = *(const LAS bf16x8*)(lds + PG8_SB(b, h) + boff + n * 2048 + k * 1024); } while (0)
; #define PG8_MMA(ai, bj, At, Bt) do { __builtin_amdgcn_s_setprio(1); _Pragma("unroll") for (int m = 0; m < 4; ++m) _Pragma("unroll") for (int n = 0; n < 2; ++n) _Pragma("unroll") for (int k = 0; k < 2; ++k) \
;         acc[ai][bj][m][n] = __builtin_amdgcn_mfma_f32_16x16x32_bf16(Bt[n][k], At[m][k], acc[ai][bj][m][n], 0, 0, 0); __builtin_amdgcn_s_setprio(0); } while (0)
; #define PG8_WAIT_L(n) asm volatile("s_waitcnt lgkmcnt(" #n ")" ::: "memory")
; #define PG8_BAR __builtin_amdgcn_s_barrier()
; template <class Epi, class Sched>
; __device__ __forceinline__ void gemm_phase(LAS unsigned char* lds, const Sched& S, const Epi& E) {
;     ...
;             const char* a1 = cA + (size_t)(t + 1) * kstep;
;             const char* a2 = last ? nA : cA + (size_t)(t + 2) * kstep; const char* b2 = last ? nB : cB + (size_t)(t + 2) * kstep;
;             const char* a3 = a2 + kstep; const char* b3 = b2 + kstep;
;             const unsigned xA0 = last ? nvA0 : vA0, xA1 = last ? nvA1 : vA1, xB0 = last ? nvB0 : vB0, xB1 = last ? nvB1 : vB1;
;             const size_t xhA = last ? nhA : hA, xhB = last ? nhB : hB;
;             PG8_LDB(B0, 0, 0); PG8_SCHED; PG8_LDA(At, 0, 0); PG8_STAGE(PG8_SA(1, 1), a1 + hA, vA0, vA1);
;             PG8_WAIT_L(8); PG8_BAR; PG8_WAIT_L(0); PG8_MMA(0, 0, At, B0); PG8_BAR; PG8_SCHED;
;             PG8_LDB(B1, 0, 1); PG8_STAGE(PG8_SB(0, 0), b2, xB0, xB1);
;             PG8_BAR; PG8_WAIT_L(0); PG8_MMA(0, 1, At, B1); PG8_BAR;
;             PG8_LDA(At, 0, 1); PG8_STAGE(PG8_SA(0, 0), a2, xA0, xA1);
;             PG8_BAR; PG8_WAIT_L(0); PG8_MMA(1, 0, At, B0); PG8_BAR; PG8_SCHED;
.LBB0_306:
	s_add_u32 s21, s26, 0xfff80080
	s_addc_u32 s69, s27, -1
	s_and_b64 s[40:41], exec, s[40:41]
	s_cselect_b32 s41, s23, s69
	s_cselect_b32 s40, s22, s21
	s_add_i32 s21, 0, 0x10000
	v_add_u32_e32 v138, s21, v153
	ds_read_b128 v[158:161], v138
	ds_read_b128 v[182:185], v138 offset:1024
	ds_read_b128 v[186:189], v138 offset:2048
	ds_read_b128 v[190:193], v138 offset:3072
	v_lshl_add_u64 v[226:227], s[26:27], 0, v[132:133]
	s_add_i32 m0, s48, 0xc000
	ds_read_b128 v[194:197], v154
	ds_read_b128 v[198:201], v154 offset:1024
	ds_read_b128 v[202:205], v154 offset:2048
	ds_read_b128 v[206:209], v154 offset:3072
	ds_read_b128 v[210:213], v154 offset:4096
	ds_read_b128 v[214:217], v154 offset:5120
	ds_read_b128 v[218:221], v154 offset:6144
	ds_read_b128 v[222:225], v154 offset:7168
	global_load_lds_dwordx4 v[226:227], off
	v_lshl_add_u64 v[226:227], s[26:27], 0, v[134:135]
	s_add_i32 m0, s48, 0xe000
	s_nop 0
	global_load_lds_dwordx4 v[226:227], off
	s_waitcnt lgkmcnt(8)
	s_barrier
	s_waitcnt lgkmcnt(0)
	s_setprio 1
	v_mfma_f32_16x16x32_bf16 v[124:127], v[158:161], v[194:197], v[124:127]
	v_mfma_f32_16x16x32_bf16 v[120:123], v[186:189], v[194:197], v[120:123]
	v_mfma_f32_16x16x32_bf16 v[116:119], v[158:161], v[202:205], v[116:119]
	v_mfma_f32_16x16x32_bf16 v[112:115], v[186:189], v[202:205], v[112:115]
	v_mfma_f32_16x16x32_bf16 v[100:103], v[158:161], v[210:213], v[100:103]
	v_mfma_f32_16x16x32_bf16 v[96:99], v[186:189], v[210:213], v[96:99]
	v_mfma_f32_16x16x32_bf16 v[84:87], v[158:161], v[218:221], v[84:87]
	v_mfma_f32_16x16x32_bf16 v[80:83], v[186:189], v[218:221], v[80:83]
	v_mfma_f32_16x16x32_bf16 v[124:127], v[182:185], v[198:201], v[124:127]
	v_mfma_f32_16x16x32_bf16 v[120:123], v[190:193], v[198:201], v[120:123]
	v_mfma_f32_16x16x32_bf16 v[116:119], v[182:185], v[206:209], v[116:119]
	v_mfma_f32_16x16x32_bf16 v[112:115], v[190:193], v[206:209], v[112:115]
	v_mfma_f32_16x16x32_bf16 v[100:103], v[182:185], v[214:217], v[100:103]
	v_mfma_f32_16x16x32_bf16 v[96:99], v[190:193], v[214:217], v[96:99]
	v_mfma_f32_16x16x32_bf16 v[84:87], v[182:185], v[222:225], v[84:87]
	v_mfma_f32_16x16x32_bf16 v[80:83], v[190:193], v[222:225], v[80:83]
	s_setprio 0
	s_barrier
	s_add_i32 s69, 0, 0x14000
	s_add_i32 s21, s21, s43
	v_add_u32_e32 v138, s69, v153
	s_mov_b32 m0, s21
	ds_read_b128 v[226:229], v138
	ds_read_b128 v[230:233], v138 offset:1024
	ds_read_b128 v[234:237], v138 offset:2048
	ds_read_b128 v[238:241], v138 offset:3072
	global_load_lds_dwordx4 v136, s[38:39]
	s_add_i32 m0, s21, 0x2000
	v_mov_b32_e32 v147, v137
	global_load_lds_dwordx4 v146, s[38:39]
	s_barrier
	s_waitcnt lgkmcnt(0)
	v_lshl_add_u64 v[242:243], s[38:39], 0, v[136:137]
	v_lshl_add_u64 v[244:245], s[38:39], 0, v[146:147]
	s_setprio 1
	v_mfma_f32_16x16x32_bf16 v[108:111], v[226:229], v[194:197], v[108:111]
	v_mfma_f32_16x16x32_bf16 v[104:107], v[234:237], v[194:197], v[104:107]
	v_mfma_f32_16x16x32_bf16 v[92:95], v[226:229], v[202:205], v[92:95]
	v_mfma_f32_16x16x32_bf16 v[88:91], v[234:237], v[202:205], v[88:91]
	v_mfma_f32_16x16x32_bf16 v[76:79], v[226:229], v[210:213], v[76:79]
	v_mfma_f32_16x16x32_bf16 v[72:75], v[234:237], v[210:213], v[72:75]
	v_mfma_f32_16x16x32_bf16 v[68:71], v[226:229], v[218:221], v[68:71]
	v_mfma_f32_16x16x32_bf16 v[64:67], v[234:237], v[218:221], v[64:67]
	v_mfma_f32_16x16x32_bf16 v[108:111], v[230:233], v[198:201], v[108:111]
	v_mfma_f32_16x16x32_bf16 v[104:107], v[238:241], v[198:201], v[104:107]
	v_mfma_f32_16x16x32_bf16 v[92:95], v[230:233], v[206:209], v[92:95]
	v_mfma_f32_16x16x32_bf16 v[88:91], v[238:241], v[206:209], v[88:91]
	v_mfma_f32_16x16x32_bf16 v[76:79], v[230:233], v[214:217], v[76:79]
	v_mfma_f32_16x16x32_bf16 v[72:75], v[238:241], v[214:217], v[72:75]
	v_mfma_f32_16x16x32_bf16 v[68:71], v[230:233], v[222:225], v[68:71]
	v_mfma_f32_16x16x32_bf16 v[64:67], v[238:241], v[222:225], v[64:67]
	s_setprio 0
	s_mov_b32 m0, s48
	v_lshl_add_u64 v[246:247], s[40:41], 0, v[150:151]
	s_barrier
	ds_read_b128 v[194:197], v154 offset:16384
	ds_read_b128 v[198:201], v154 offset:17408
	ds_read_b128 v[202:205], v154 offset:18432
	ds_read_b128 v[206:209], v154 offset:19456
	ds_read_b128 v[210:213], v154 offset:20480
	ds_read_b128 v[214:217], v154 offset:21504
	ds_read_b128 v[218:221], v154 offset:22528
	ds_read_b128 v[222:225], v154 offset:23552
	global_load_lds_dwordx4 v[246:247], off
	v_lshl_add_u64 v[248:249], s[40:41], 0, v[148:149]
	s_mov_b32 m0, s49
	s_nop 0
	global_load_lds_dwordx4 v[248:249], off
	s_barrier
	s_waitcnt lgkmcnt(0)
	s_setprio 1
	v_mfma_f32_16x16x32_bf16 v[60:63], v[158:161], v[194:197], v[60:63]
	v_mfma_f32_16x16x32_bf16 v[56:59], v[186:189], v[194:197], v[56:59]
	v_mfma_f32_16x16x32_bf16 v[52:55], v[158:161], v[202:205], v[52:55]
	v_mfma_f32_16x16x32_bf16 v[44:47], v[186:189], v[202:205], v[44:47]
	v_mfma_f32_16x16x32_bf16 v[36:39], v[158:161], v[210:213], v[36:39]
	v_mfma_f32_16x16x32_bf16 v[28:31], v[186:189], v[210:213], v[28:31]
	v_mfma_f32_16x16x32_bf16 v[20:23], v[158:161], v[218:221], v[20:23]
	v_mfma_f32_16x16x32_bf16 v[12:15], v[186:189], v[218:221], v[12:15]
	v_mfma_f32_16x16x32_bf16 v[60:63], v[182:185], v[198:201], v[60:63]
	v_mfma_f32_16x16x32_bf16 v[56:59], v[190:193], v[198:201], v[56:59]
	v_mfma_f32_16x16x32_bf16 v[52:55], v[182:185], v[206:209], v[52:55]
	v_mfma_f32_16x16x32_bf16 v[44:47], v[190:193], v[206:209], v[44:47]
	v_mfma_f32_16x16x32_bf16 v[36:39], v[182:185], v[214:217], v[36:39]
	v_mfma_f32_16x16x32_bf16 v[28:31], v[190:193], v[214:217], v[28:31]
	v_mfma_f32_16x16x32_bf16 v[20:23], v[182:185], v[222:225], v[20:23]
	v_mfma_f32_16x16x32_bf16 v[12:15], v[190:193], v[222:225], v[12:15]
	s_setprio 0
	s_barrier
; #define PG8_STAGE(bufoff, gbase, v0, v1) do { \
;         __builtin_amdgcn_global_load_lds((const unsigned*)((const char*)(gbase) + (v0)), (LAS unsigned*)(lds + (bufoff) + ldsw), 16, 0, 0); \
;         __builtin_amdgcn_global_load_lds((const unsigned*)((const char*)(gbase) + (v1)), (LAS unsigned*)(lds + (bufoff) + ldsw + 8192), 16, 0, 0); } while (0)
; #define PG8_LDA(dst, b, h) do { _Pragma("unroll") for (int m = 0; m < 4; ++m) _Pragma("unroll") for (int k = 0; k < 2; ++k) dst[m][k] = *(const LAS bf16x8*)(lds + PG8_SA(b, h) + aoff + m * 2048 + k * 1024); } while (0)
; #define PG8_LDB(dst, b, h) do { _Pragma("unroll") for (int n = 0; n < 2; ++n) _Pragma("unroll") for (int k = 0; k < 2; ++k) dst[n][k] = *(const LAS bf16x8*)(lds + PG8_SB(b, h) + boff + n * 2048 + k * 1024); } while (0)
; #define PG8_MMA(ai, bj, At, Bt) do { __builtin_amdgcn_s_setprio(1); _Pragma("unroll") for (int m = 0; m < 4; ++m) _Pragma("unroll") for (int n = 0; n < 2; ++n) _Pragma("unroll") for (int k = 0; k < 2; ++k) \
;         acc[ai][bj][m][n] = __builtin_amdgcn_mfma_f32_16x16x32_bf16(Bt[n][k], At[m][k], acc[ai][bj][m][n], 0, 0, 0); __builtin_amdgcn_s_setprio(0); } while (0)
; #define PG8_WAIT_V(n) asm volatile("s_waitcnt vmcnt(" #n ")" ::: "memory")
; #define PG8_WAIT_L(n) asm volatile("s_waitcnt lgkmcnt(" #n ")" ::: "memory")
; #define PG8_BAR __builtin_amdgcn_s_barrier()
; #define PG8_SCHED __builtin_amdgcn_sched_barrier(0)
; template <class Epi, class Sched>
; __device__ __forceinline__ void gemm_phase(LAS unsigned char* lds, const Sched& S, const Epi& E) {
;     ...
;             PG8_STAGE(PG8_SB(0, 1), b2 + xhB, xB0, xB1);
;             PG8_WAIT_V(6); PG8_BAR; PG8_MMA(1, 1, At, B1); PG8_BAR;
;             PG8_LDB(B0, 1, 0); PG8_SCHED; PG8_LDA(At, 1, 0); PG8_STAGE(PG8_SA(0, 1), a2 + xhA, xA0, xA1);
;             PG8_WAIT_L(8); PG8_BAR; PG8_WAIT_L(0); PG8_MMA(0, 0, At, B0); PG8_BAR; PG8_SCHED;
;             PG8_LDB(B1, 1, 1); PG8_STAGE(PG8_SB(1, 0), b3, xB0, xB1);
	s_add_u32 s70, s38, 0x80000
	s_addc_u32 s71, s39, 0
	s_add_i32 s21, s69, s43
	s_mov_b32 m0, s21
	s_nop 0
	global_load_lds_dwordx4 v136, s[70:71]
	s_add_i32 m0, s21, 0x2000
	s_nop 0
	global_load_lds_dwordx4 v146, s[70:71]
	s_add_i32 s21, 0, 0x18000
	v_add_u32_e32 v138, s21, v153
	s_waitcnt vmcnt(6)
	s_barrier
	s_setprio 1
	v_mfma_f32_16x16x32_bf16 v[48:51], v[226:229], v[194:197], v[48:51]
	ds_read_b128 v[158:161], v138
	v_mfma_f32_16x16x32_bf16 v[40:43], v[234:237], v[194:197], v[40:43]
	ds_read_b128 v[182:185], v138 offset:1024
	v_mfma_f32_16x16x32_bf16 v[32:35], v[226:229], v[202:205], v[32:35]
	ds_read_b128 v[186:189], v138 offset:2048
	v_mfma_f32_16x16x32_bf16 v[24:27], v[234:237], v[202:205], v[24:27]
	ds_read_b128 v[190:193], v138 offset:3072
	v_mfma_f32_16x16x32_bf16 v[16:19], v[226:229], v[210:213], v[16:19]
	v_mfma_f32_16x16x32_bf16 v[8:11], v[234:237], v[210:213], v[8:11]
	v_mfma_f32_16x16x32_bf16 v[4:7], v[226:229], v[218:221], v[4:7]
	v_mfma_f32_16x16x32_bf16 v[0:3], v[234:237], v[218:221], v[0:3]
	v_mfma_f32_16x16x32_bf16 v[48:51], v[230:233], v[198:201], v[48:51]
	v_mfma_f32_16x16x32_bf16 v[40:43], v[238:241], v[198:201], v[40:43]
	v_mfma_f32_16x16x32_bf16 v[32:35], v[230:233], v[206:209], v[32:35]
	v_mfma_f32_16x16x32_bf16 v[24:27], v[238:241], v[206:209], v[24:27]
	v_mfma_f32_16x16x32_bf16 v[16:19], v[230:233], v[214:217], v[16:19]
	v_mfma_f32_16x16x32_bf16 v[8:11], v[238:241], v[214:217], v[8:11]
	v_mfma_f32_16x16x32_bf16 v[4:7], v[230:233], v[222:225], v[4:7]
	v_mfma_f32_16x16x32_bf16 v[0:3], v[238:241], v[222:225], v[0:3]
	s_setprio 0
	s_barrier
	s_add_u32 s40, s40, 0x80000
	s_addc_u32 s41, s41, 0
	s_mov_b32 m0, s50
	v_lshl_add_u64 v[150:151], s[40:41], 0, v[150:151]
	ds_read_b128 v[194:197], v154 offset:32768
	ds_read_b128 v[198:201], v154 offset:33792
	ds_read_b128 v[202:205], v154 offset:34816
	ds_read_b128 v[206:209], v154 offset:35840
	ds_read_b128 v[210:213], v154 offset:36864
	ds_read_b128 v[214:217], v154 offset:37888
	ds_read_b128 v[218:221], v154 offset:38912
	ds_read_b128 v[222:225], v154 offset:39936
	global_load_lds_dwordx4 v[150:151], off
	v_lshl_add_u64 v[148:149], s[40:41], 0, v[148:149]
	s_mov_b32 m0, s51
	s_nop 0
	global_load_lds_dwordx4 v[148:149], off
	s_waitcnt lgkmcnt(8)
	s_barrier
	s_waitcnt lgkmcnt(0)
	s_setprio 1
	v_mfma_f32_16x16x32_bf16 v[124:127], v[158:161], v[194:197], v[124:127]
	v_mfma_f32_16x16x32_bf16 v[120:123], v[186:189], v[194:197], v[120:123]
	v_mfma_f32_16x16x32_bf16 v[116:119], v[158:161], v[202:205], v[116:119]
	v_mfma_f32_16x16x32_bf16 v[112:115], v[186:189], v[202:205], v[112:115]
	v_mfma_f32_16x16x32_bf16 v[100:103], v[158:161], v[210:213], v[100:103]
	v_mfma_f32_16x16x32_bf16 v[96:99], v[186:189], v[210:213], v[96:99]
	v_mfma_f32_16x16x32_bf16 v[84:87], v[158:161], v[218:221], v[84:87]
	v_mfma_f32_16x16x32_bf16 v[80:83], v[186:189], v[218:221], v[80:83]
	v_mfma_f32_16x16x32_bf16 v[124:127], v[182:185], v[198:201], v[124:127]
	v_mfma_f32_16x16x32_bf16 v[120:123], v[190:193], v[198:201], v[120:123]
	v_mfma_f32_16x16x32_bf16 v[116:119], v[182:185], v[206:209], v[116:119]
	v_mfma_f32_16x16x32_bf16 v[112:115], v[190:193], v[206:209], v[112:115]
	v_mfma_f32_16x16x32_bf16 v[100:103], v[182:185], v[214:217], v[100:103]
	v_mfma_f32_16x16x32_bf16 v[96:99], v[190:193], v[214:217], v[96:99]
	v_mfma_f32_16x16x32_bf16 v[84:87], v[182:185], v[222:225], v[84:87]
	v_mfma_f32_16x16x32_bf16 v[80:83], v[190:193], v[222:225], v[80:83]
	s_setprio 0
	s_barrier
	s_add_i32 s40, 0, 0x1c000
	s_add_i32 s21, s21, s43
	v_add_u32_e32 v138, s40, v153
	v_lshl_add_u64 v[238:239], v[242:243], 0, s[44:45]
	s_mov_b32 m0, s21
	ds_read_b128 v[148:151], v138
	ds_read_b128 v[226:229], v138 offset:1024
	ds_read_b128 v[230:233], v138 offset:2048
	ds_read_b128 v[234:237], v138 offset:3072
	global_load_lds_dwordx4 v[238:239], off
	v_lshl_add_u64 v[238:239], v[244:245], 0, s[44:45]
	s_add_i32 m0, s21, 0x2000
	s_nop 0
	global_load_lds_dwordx4 v[238:239], off
	s_barrier
; #define PG8_STAGE(bufoff, gbase, v0, v1) do { \
;         __builtin_amdgcn_global_load_lds((const unsigned*)((const char*)(gbase) + (v0)), (LAS unsigned*)(lds + (bufoff) + ldsw), 16, 0, 0); \
;         __builtin_amdgcn_global_load_lds((const unsigned*)((const char*)(gbase) + (v1)), (LAS unsigned*)(lds + (bufoff) + ldsw + 8192), 16, 0, 0); } while (0)
; #define PG8_LDA(dst, b, h) do { _Pragma("unroll") for (int m = 0; m < 4; ++m) _Pragma("unroll") for (int k = 0; k < 2; ++k) dst[m][k] = *(const LAS bf16x8*)(lds + PG8_SA(b, h) + aoff + m * 2048 + k * 1024); } while (0)
; #define PG8_MMA(ai, bj, At, Bt) do { __builtin_amdgcn_s_setprio(1); _Pragma("unroll") for (int m = 0; m < 4; ++m) _Pragma("unroll") for (int n = 0; n < 2; ++n) _Pragma("unroll") for (int k = 0; k < 2; ++k) \
;         acc[ai][bj][m][n] = __builtin_amdgcn_mfma_f32_16x16x32_bf16(Bt[n][k], At[m][k], acc[ai][bj][m][n], 0, 0, 0); __builtin_amdgcn_s_setprio(0); } while (0)
; #define PG8_WAIT_V(n) asm volatile("s_waitcnt vmcnt(" #n ")" ::: "memory")
; #define PG8_WAIT_L(n) asm volatile("s_waitcnt lgkmcnt(" #n ")" ::: "memory")
; #define PG8_BAR __builtin_amdgcn_s_barrier()
; #define PG8_SCHED __builtin_amdgcn_sched_barrier(0)
; template <class Epi, class Sched>
; __device__ __forceinline__ void gemm_phase(LAS unsigned char* lds, const Sched& S, const Epi& E) {
;     ...
;         for (int t = 0; t < nt; t += 2) {
;             const bool last = (t == nt - 2);
;             const char* a1 = cA + (size_t)(t + 1) * kstep;
;             const char* a2 = last ? nA : cA + (size_t)(t + 2) * kstep; const char* b2 = last ? nB : cB + (size_t)(t + 2) * kstep;
;             const char* a3 = a2 + kstep; const char* b3 = b2 + kstep;
;             const unsigned xA0 = last ? nvA0 : vA0, xA1 = last ? nvA1 : vA1, xB0 = last ? nvB0 : vB0, xB1 = last ? nvB1 : vB1;
;             const size_t xhA = last ? nhA : hA, xhB = last ? nhB : hB;
;     ...
;             PG8_BAR; PG8_WAIT_L(0); PG8_MMA(0, 1, At, B1); PG8_BAR;
;             PG8_LDA(At, 1, 1); PG8_STAGE(PG8_SA(1, 0), a3, xA0, xA1);
;             PG8_BAR; PG8_WAIT_L(0); PG8_MMA(1, 0, At, B0); PG8_BAR; PG8_SCHED;
;             PG8_STAGE(PG8_SB(1, 1), b3 + xhB, xB0, xB1);
;             PG8_WAIT_V(6); PG8_BAR; PG8_MMA(1, 1, At, B1); PG8_BAR;
	s_waitcnt lgkmcnt(0)
	s_setprio 1
	v_mfma_f32_16x16x32_bf16 v[108:111], v[148:151], v[194:197], v[108:111]
	v_mfma_f32_16x16x32_bf16 v[104:107], v[230:233], v[194:197], v[104:107]
	v_mfma_f32_16x16x32_bf16 v[92:95], v[148:151], v[202:205], v[92:95]
	v_mfma_f32_16x16x32_bf16 v[88:91], v[230:233], v[202:205], v[88:91]
	v_mfma_f32_16x16x32_bf16 v[76:79], v[148:151], v[210:213], v[76:79]
	v_mfma_f32_16x16x32_bf16 v[72:75], v[230:233], v[210:213], v[72:75]
	v_mfma_f32_16x16x32_bf16 v[68:71], v[148:151], v[218:221], v[68:71]
	v_mfma_f32_16x16x32_bf16 v[64:67], v[230:233], v[218:221], v[64:67]
	v_mfma_f32_16x16x32_bf16 v[108:111], v[226:229], v[198:201], v[108:111]
	v_mfma_f32_16x16x32_bf16 v[104:107], v[234:237], v[198:201], v[104:107]
	v_mfma_f32_16x16x32_bf16 v[92:95], v[226:229], v[206:209], v[92:95]
	v_mfma_f32_16x16x32_bf16 v[88:91], v[234:237], v[206:209], v[88:91]
	v_mfma_f32_16x16x32_bf16 v[76:79], v[226:229], v[214:217], v[76:79]
	v_mfma_f32_16x16x32_bf16 v[72:75], v[234:237], v[214:217], v[72:75]
	v_mfma_f32_16x16x32_bf16 v[68:71], v[226:229], v[222:225], v[68:71]
	v_mfma_f32_16x16x32_bf16 v[64:67], v[234:237], v[222:225], v[64:67]
	s_setprio 0
	s_mov_b32 m0, s64
	v_lshl_add_u64 v[238:239], v[246:247], 0, s[44:45]
	s_barrier
	ds_read_b128 v[194:197], v154 offset:49152
	ds_read_b128 v[198:201], v154 offset:50176
	ds_read_b128 v[202:205], v154 offset:51200
	ds_read_b128 v[206:209], v154 offset:52224
	ds_read_b128 v[210:213], v154 offset:53248
	ds_read_b128 v[214:217], v154 offset:54272
	ds_read_b128 v[218:221], v154 offset:55296
	ds_read_b128 v[222:225], v154 offset:56320
	global_load_lds_dwordx4 v[238:239], off
	v_lshl_add_u64 v[238:239], v[248:249], 0, s[44:45]
	s_mov_b32 m0, s65
	s_nop 0
	global_load_lds_dwordx4 v[238:239], off
	s_barrier
	s_waitcnt lgkmcnt(0)
	s_setprio 1
	v_mfma_f32_16x16x32_bf16 v[60:63], v[158:161], v[194:197], v[60:63]
	v_mfma_f32_16x16x32_bf16 v[56:59], v[186:189], v[194:197], v[56:59]
	v_mfma_f32_16x16x32_bf16 v[52:55], v[158:161], v[202:205], v[52:55]
	v_mfma_f32_16x16x32_bf16 v[44:47], v[186:189], v[202:205], v[44:47]
	v_mfma_f32_16x16x32_bf16 v[36:39], v[158:161], v[210:213], v[36:39]
	v_mfma_f32_16x16x32_bf16 v[28:31], v[186:189], v[210:213], v[28:31]
	v_mfma_f32_16x16x32_bf16 v[20:23], v[158:161], v[218:221], v[20:23]
	v_mfma_f32_16x16x32_bf16 v[12:15], v[186:189], v[218:221], v[12:15]
	v_mfma_f32_16x16x32_bf16 v[60:63], v[182:185], v[198:201], v[60:63]
	v_mfma_f32_16x16x32_bf16 v[56:59], v[190:193], v[198:201], v[56:59]
	v_mfma_f32_16x16x32_bf16 v[52:55], v[182:185], v[206:209], v[52:55]
	v_mfma_f32_16x16x32_bf16 v[44:47], v[190:193], v[206:209], v[44:47]
	v_mfma_f32_16x16x32_bf16 v[36:39], v[182:185], v[214:217], v[36:39]
	v_mfma_f32_16x16x32_bf16 v[28:31], v[190:193], v[214:217], v[28:31]
	v_mfma_f32_16x16x32_bf16 v[20:23], v[182:185], v[222:225], v[20:23]
	v_mfma_f32_16x16x32_bf16 v[12:15], v[190:193], v[222:225], v[12:15]
	s_setprio 0
	s_barrier
	s_add_u32 s38, s38, 0x80080
	s_addc_u32 s39, s39, 0
	s_add_i32 s21, s40, s43
	s_mov_b32 m0, s21
	s_nop 0
	global_load_lds_dwordx4 v136, s[38:39]
	s_add_i32 m0, s21, 0x2000
	s_nop 0
	global_load_lds_dwordx4 v146, s[38:39]
	s_waitcnt vmcnt(6)
	s_barrier
	s_setprio 1
	v_mfma_f32_16x16x32_bf16 v[48:51], v[148:151], v[194:197], v[48:51]
	v_mfma_f32_16x16x32_bf16 v[40:43], v[230:233], v[194:197], v[40:43]
	v_mfma_f32_16x16x32_bf16 v[32:35], v[148:151], v[202:205], v[32:35]
	v_mfma_f32_16x16x32_bf16 v[24:27], v[230:233], v[202:205], v[24:27]
	v_mfma_f32_16x16x32_bf16 v[16:19], v[148:151], v[210:213], v[16:19]
	v_mfma_f32_16x16x32_bf16 v[8:11], v[230:233], v[210:213], v[8:11]
	v_mfma_f32_16x16x32_bf16 v[4:7], v[148:151], v[218:221], v[4:7]
	v_mfma_f32_16x16x32_bf16 v[0:3], v[230:233], v[218:221], v[0:3]
	v_mfma_f32_16x16x32_bf16 v[48:51], v[226:229], v[198:201], v[48:51]
	v_mfma_f32_16x16x32_bf16 v[40:43], v[234:237], v[198:201], v[40:43]
	v_mfma_f32_16x16x32_bf16 v[32:35], v[226:229], v[206:209], v[32:35]
	v_mfma_f32_16x16x32_bf16 v[24:27], v[234:237], v[206:209], v[24:27]
	v_mfma_f32_16x16x32_bf16 v[16:19], v[226:229], v[214:217], v[16:19]
	v_mfma_f32_16x16x32_bf16 v[8:11], v[234:237], v[214:217], v[8:11]
	v_mfma_f32_16x16x32_bf16 v[4:7], v[226:229], v[222:225], v[4:7]
	v_mfma_f32_16x16x32_bf16 v[0:3], v[234:237], v[222:225], v[0:3]
	s_setprio 0
	s_add_i32 s15, s15, 2
	s_add_u32 s26, s26, 0x100
	s_addc_u32 s27, s27, 0
	s_add_u32 s34, s34, 0x100
	s_addc_u32 s35, s35, 0
	s_cmp_gt_u32 s15, 29
	s_cbranch_scc1 .Lrot_exit_0
	s_cmp_eq_u32 s15, 28
	s_cselect_b64 s[40:41], -1, 0
	s_and_b64 vcc, exec, s[40:41]
	v_mov_b64_e32 v[148:149], v[130:131]
	v_mov_b64_e32 v[150:151], v[128:129]
	v_mov_b32_e32 v146, v156
	v_mov_b32_e32 v136, v155
	s_mov_b64 s[38:39], s[24:25]
	s_cbranch_vccnz .Lrot_join_0
	v_mov_b64_e32 v[148:149], v[134:135]
	v_mov_b64_e32 v[150:151], v[132:133]
	v_mov_b32_e32 v146, v142
	v_mov_b32_e32 v136, v144
	s_mov_b64 s[38:39], s[34:35]

; #define PG8_STAGE(bufoff, gbase, v0, v1) do { \
;         __builtin_amdgcn_global_load_lds((const unsigned*)((const char*)(gbase) + (v0)), (LAS unsigned*)(lds + (bufoff) + ldsw), 16, 0, 0); \
;         __builtin_amdgcn_global_load_lds((const unsigned*)((const char*)(gbase) + (v1)), (LAS unsigned*)(lds + (bufoff) + ldsw + 8192), 16, 0, 0); } while (0)
; #define PG8_LDA(dst, b, h) do { _Pragma("unroll") for (int m = 0; m < 4; ++m) _Pragma("unroll") for (int k = 0; k < 2; ++k) dst[m][k] = *(const LAS bf16x8*)(lds + PG8_SA(b, h) + aoff + m * 2048 + k * 1024); } while (0)
; #define PG8_WAIT_L(n) asm volatile("s_waitcnt lgkmcnt(" #n ")" ::: "memory")
;     __device__ bool next(int i, GUnit& u) const {
;         const int ti = i / 6, sub = i - ti * 6, br = sub >> 1;
;         int pm, pn; if (!T.tile(ti, pm, pn)) return false;
;         u.pm = pm; u.pn = pn; u.sub = sub;
;         if ((sub & 1) == 0) { u.A = H + (size_t)pm * BM * 4096; u.lda = 4096; u.B = Wg + ((size_t)br * 2048 + (size_t)pn * BM) * 4096; u.ldb = 4096; u.nt = 32; }
;         else { const int col = br == 0 ? AQ : (br == 1 ? BG : CG);
;             u.A = PROJ + (size_t)pm * BM * (INW * 2) + col * 2; u.lda = INW * 2; u.B = Wbr + (size_t)br * 2048 * 2048 + (size_t)pn * BM * 2048; u.ldb = 2048; u.nt = 16; }
; template <class Epi, class Sched>
; __device__ __forceinline__ void gemm_phase(LAS unsigned char* lds, const Sched& S, const Epi& E) {
;     ...
;             const char* a1 = cA + (size_t)(t + 1) * kstep;
;             const char* a2 = last ? nA : cA + (size_t)(t + 2) * kstep; const char* b2 = last ? nB : cB + (size_t)(t + 2) * kstep;
;             const char* a3 = a2 + kstep; const char* b3 = b2 + kstep;
;             const unsigned xA0 = last ? nvA0 : vA0, xA1 = last ? nvA1 : vA1, xB0 = last ? nvB0 : vB0, xB1 = last ? nvB1 : vB1;
;             const size_t xhA = last ? nhA : hA, xhB = last ? nhB : hB;
;             PG8_LDB(B0, 0, 0); PG8_SCHED; PG8_LDA(At, 0, 0); PG8_STAGE(PG8_SA(1, 1), a1 + hA, vA0, vA1);
;             PG8_WAIT_L(8); PG8_BAR; PG8_WAIT_L(0); PG8_MMA(0, 0, At, B0); PG8_BAR; PG8_SCHED;
;             PG8_LDB(B1, 0, 1); PG8_STAGE(PG8_SB(0, 0), b2, xB0, xB1);
;             PG8_BAR; PG8_WAIT_L(0); PG8_MMA(0, 1, At, B1); PG8_BAR;
;             PG8_LDA(At, 0, 1); PG8_STAGE(PG8_SA(0, 0), a2, xA0, xA1);
;             PG8_BAR; PG8_WAIT_L(0); PG8_MMA(1, 0, At, B0); PG8_BAR; PG8_SCHED;
.LBB0_574:
	s_add_i32 s49, s49, 2
	s_add_u32 s65, s34, 0x80
	s_addc_u32 vcc_lo, s35, 0
	s_and_b64 s[54:55], exec, s[54:55]
	s_cselect_b32 s55, s41, vcc_lo
	s_cselect_b32 s54, s40, s65
	s_add_i32 s65, 0, 0x10000
	v_add_u32_e32 v138, s65, v184
	ds_read_b128 v[158:161], v138
	ds_read_b128 v[186:189], v138 offset:1024
	ds_read_b128 v[190:193], v138 offset:2048
	ds_read_b128 v[194:197], v138 offset:3072
	v_lshl_add_u64 v[230:231], s[34:35], 0, v[134:135]
	s_add_i32 m0, s91, 0xc000
	ds_read_b128 v[198:201], v185
	ds_read_b128 v[202:205], v185 offset:1024
	ds_read_b128 v[206:209], v185 offset:2048
	ds_read_b128 v[210:213], v185 offset:3072
	ds_read_b128 v[214:217], v185 offset:4096
	ds_read_b128 v[218:221], v185 offset:5120
	ds_read_b128 v[222:225], v185 offset:6144
	ds_read_b128 v[226:229], v185 offset:7168
	global_load_lds_dwordx4 v[230:231], off
	v_lshl_add_u64 v[230:231], s[34:35], 0, v[150:151]
	s_add_i32 m0, s91, 0xe000
	s_nop 0
	global_load_lds_dwordx4 v[230:231], off
	s_waitcnt lgkmcnt(8)
	s_barrier
	s_waitcnt lgkmcnt(0)
	s_setprio 1
	v_mfma_f32_16x16x32_bf16 v[124:127], v[158:161], v[198:201], v[124:127]
	v_mfma_f32_16x16x32_bf16 v[120:123], v[190:193], v[198:201], v[120:123]
	v_mfma_f32_16x16x32_bf16 v[116:119], v[158:161], v[206:209], v[116:119]
	v_mfma_f32_16x16x32_bf16 v[112:115], v[190:193], v[206:209], v[112:115]
	v_mfma_f32_16x16x32_bf16 v[108:111], v[158:161], v[214:217], v[108:111]
	v_mfma_f32_16x16x32_bf16 v[104:107], v[190:193], v[214:217], v[104:107]
	v_mfma_f32_16x16x32_bf16 v[100:103], v[158:161], v[222:225], v[100:103]
	v_mfma_f32_16x16x32_bf16 v[96:99], v[190:193], v[222:225], v[96:99]
	v_mfma_f32_16x16x32_bf16 v[124:127], v[186:189], v[202:205], v[124:127]
	v_mfma_f32_16x16x32_bf16 v[120:123], v[194:197], v[202:205], v[120:123]
	v_mfma_f32_16x16x32_bf16 v[116:119], v[186:189], v[210:213], v[116:119]
	v_mfma_f32_16x16x32_bf16 v[112:115], v[194:197], v[210:213], v[112:115]
	v_mfma_f32_16x16x32_bf16 v[108:111], v[186:189], v[218:221], v[108:111]
	v_mfma_f32_16x16x32_bf16 v[104:107], v[194:197], v[218:221], v[104:107]
	v_mfma_f32_16x16x32_bf16 v[100:103], v[186:189], v[226:229], v[100:103]
	v_mfma_f32_16x16x32_bf16 v[96:99], v[194:197], v[226:229], v[96:99]
	s_setprio 0
	s_barrier
	s_add_i32 vcc_lo, 0, 0x14000
	s_add_i32 s65, s65, s9
	v_add_u32_e32 v138, vcc_lo, v184
	s_mov_b32 m0, s65
	ds_read_b128 v[230:233], v138
	ds_read_b128 v[234:237], v138 offset:1024
	ds_read_b128 v[238:241], v138 offset:2048
	ds_read_b128 v[242:245], v138 offset:3072
	global_load_lds_dwordx4 v136, s[92:93]
	s_add_i32 m0, s65, 0x2000
	v_mov_b32_e32 v157, v137
	global_load_lds_dwordx4 v156, s[92:93]
	s_barrier
	s_waitcnt lgkmcnt(0)
	v_lshl_add_u64 v[246:247], s[92:93], 0, v[136:137]
	v_lshl_add_u64 v[248:249], s[92:93], 0, v[156:157]
	s_setprio 1
	v_mfma_f32_16x16x32_bf16 v[92:95], v[230:233], v[198:201], v[92:95]
	v_mfma_f32_16x16x32_bf16 v[88:91], v[238:241], v[198:201], v[88:91]
	v_mfma_f32_16x16x32_bf16 v[84:87], v[230:233], v[206:209], v[84:87]
	v_mfma_f32_16x16x32_bf16 v[80:83], v[238:241], v[206:209], v[80:83]
	v_mfma_f32_16x16x32_bf16 v[76:79], v[230:233], v[214:217], v[76:79]
	v_mfma_f32_16x16x32_bf16 v[72:75], v[238:241], v[214:217], v[72:75]
	v_mfma_f32_16x16x32_bf16 v[68:71], v[230:233], v[222:225], v[68:71]
	v_mfma_f32_16x16x32_bf16 v[64:67], v[238:241], v[222:225], v[64:67]
	v_mfma_f32_16x16x32_bf16 v[92:95], v[234:237], v[202:205], v[92:95]
	v_mfma_f32_16x16x32_bf16 v[88:91], v[242:245], v[202:205], v[88:91]
	v_mfma_f32_16x16x32_bf16 v[84:87], v[234:237], v[210:213], v[84:87]
	v_mfma_f32_16x16x32_bf16 v[80:83], v[242:245], v[210:213], v[80:83]
	v_mfma_f32_16x16x32_bf16 v[76:79], v[234:237], v[218:221], v[76:79]
	v_mfma_f32_16x16x32_bf16 v[72:75], v[242:245], v[218:221], v[72:75]
	v_mfma_f32_16x16x32_bf16 v[68:71], v[234:237], v[226:229], v[68:71]
	v_mfma_f32_16x16x32_bf16 v[64:67], v[242:245], v[226:229], v[64:67]
	s_setprio 0
	s_mov_b32 m0, s91
	v_lshl_add_u64 v[250:251], s[54:55], 0, v[154:155]
	s_barrier
	ds_read_b128 v[198:201], v185 offset:16384
	ds_read_b128 v[202:205], v185 offset:17408
	ds_read_b128 v[206:209], v185 offset:18432
	ds_read_b128 v[210:213], v185 offset:19456
	ds_read_b128 v[214:217], v185 offset:20480
	ds_read_b128 v[218:221], v185 offset:21504
	ds_read_b128 v[222:225], v185 offset:22528
	ds_read_b128 v[226:229], v185 offset:23552
	global_load_lds_dwordx4 v[250:251], off
	v_lshl_add_u64 v[140:141], s[54:55], 0, v[152:153]
	s_mov_b32 m0, s50
	s_nop 0
	global_load_lds_dwordx4 v[140:141], off
	s_barrier
	s_waitcnt lgkmcnt(0)
	s_setprio 1
	v_mfma_f32_16x16x32_bf16 v[60:63], v[158:161], v[198:201], v[60:63]
	v_mfma_f32_16x16x32_bf16 v[56:59], v[190:193], v[198:201], v[56:59]
	v_mfma_f32_16x16x32_bf16 v[52:55], v[158:161], v[206:209], v[52:55]
	v_mfma_f32_16x16x32_bf16 v[48:51], v[190:193], v[206:209], v[48:51]
	v_mfma_f32_16x16x32_bf16 v[44:47], v[158:161], v[214:217], v[44:47]
	v_mfma_f32_16x16x32_bf16 v[40:43], v[190:193], v[214:217], v[40:43]
	v_mfma_f32_16x16x32_bf16 v[36:39], v[158:161], v[222:225], v[36:39]
	v_mfma_f32_16x16x32_bf16 v[32:35], v[190:193], v[222:225], v[32:35]
	v_mfma_f32_16x16x32_bf16 v[60:63], v[186:189], v[202:205], v[60:63]
	v_mfma_f32_16x16x32_bf16 v[56:59], v[194:197], v[202:205], v[56:59]
	v_mfma_f32_16x16x32_bf16 v[52:55], v[186:189], v[210:213], v[52:55]
	v_mfma_f32_16x16x32_bf16 v[48:51], v[194:197], v[210:213], v[48:51]
	v_mfma_f32_16x16x32_bf16 v[44:47], v[186:189], v[218:221], v[44:47]
	v_mfma_f32_16x16x32_bf16 v[40:43], v[194:197], v[218:221], v[40:43]
	v_mfma_f32_16x16x32_bf16 v[36:39], v[186:189], v[226:229], v[36:39]
	v_mfma_f32_16x16x32_bf16 v[32:35], v[194:197], v[226:229], v[32:35]
	s_setprio 0
	s_barrier
; #define PG8_STAGE(bufoff, gbase, v0, v1) do { \
;         __builtin_amdgcn_global_load_lds((const unsigned*)((const char*)(gbase) + (v0)), (LAS unsigned*)(lds + (bufoff) + ldsw), 16, 0, 0); \
;         __builtin_amdgcn_global_load_lds((const unsigned*)((const char*)(gbase) + (v1)), (LAS unsigned*)(lds + (bufoff) + ldsw + 8192), 16, 0, 0); } while (0)
; #define PG8_LDA(dst, b, h) do { _Pragma("unroll") for (int m = 0; m < 4; ++m) _Pragma("unroll") for (int k = 0; k < 2; ++k) dst[m][k] = *(const LAS bf16x8*)(lds + PG8_SA(b, h) + aoff + m * 2048 + k * 1024); } while (0)
; #define PG8_LDB(dst, b, h) do { _Pragma("unroll") for (int n = 0; n < 2; ++n) _Pragma("unroll") for (int k = 0; k < 2; ++k) dst[n][k] = *(const LAS bf16x8*)(lds + PG8_SB(b, h) + boff + n * 2048 + k * 1024); } while (0)
; #define PG8_MMA(ai, bj, At, Bt) do { __builtin_amdgcn_s_setprio(1); _Pragma("unroll") for (int m = 0; m < 4; ++m) _Pragma("unroll") for (int n = 0; n < 2; ++n) _Pragma("unroll") for (int k = 0; k < 2; ++k) \
;         acc[ai][bj][m][n] = __builtin_amdgcn_mfma_f32_16x16x32_bf16(Bt[n][k], At[m][k], acc[ai][bj][m][n], 0, 0, 0); __builtin_amdgcn_s_setprio(0); } while (0)
; #define PG8_WAIT_V(n) asm volatile("s_waitcnt vmcnt(" #n ")" ::: "memory")
; #define PG8_WAIT_L(n) asm volatile("s_waitcnt lgkmcnt(" #n ")" ::: "memory")
; #define PG8_BAR __builtin_amdgcn_s_barrier()
; #define PG8_SCHED __builtin_amdgcn_sched_barrier(0)
; template <class Epi, class Sched>
; __device__ __forceinline__ void gemm_phase(LAS unsigned char* lds, const Sched& S, const Epi& E) {
;     ...
;             PG8_STAGE(PG8_SB(0, 1), b2 + xhB, xB0, xB1);
;             PG8_WAIT_V(6); PG8_BAR; PG8_MMA(1, 1, At, B1); PG8_BAR;
;             PG8_LDB(B0, 1, 0); PG8_SCHED; PG8_LDA(At, 1, 0); PG8_STAGE(PG8_SA(0, 1), a2 + xhA, xA0, xA1);
;             PG8_WAIT_L(8); PG8_BAR; PG8_WAIT_L(0); PG8_MMA(0, 0, At, B0); PG8_BAR; PG8_SCHED;
;             PG8_LDB(B1, 1, 1); PG8_STAGE(PG8_SB(1, 0), b3, xB0, xB1);
	s_add_u32 s88, s92, s88
	s_addc_u32 s89, s93, s89
	s_add_i32 s65, vcc_lo, s9
	s_mov_b32 m0, s65
	v_lshl_add_u64 v[160:161], s[88:89], 0, v[136:137]
	global_load_lds_dwordx4 v136, s[88:89]
	s_add_i32 m0, s65, 0x2000
	v_lshl_add_u64 v[138:139], s[88:89], 0, v[156:157]
	global_load_lds_dwordx4 v156, s[88:89]
	s_add_i32 s65, 0, 0x18000
	v_add_u32_e32 v136, s65, v184
	s_waitcnt vmcnt(6)
	s_barrier
	s_setprio 1
	v_mfma_f32_16x16x32_bf16 v[28:31], v[230:233], v[198:201], v[28:31]
	ds_read_b128 v[156:159], v136
	v_mfma_f32_16x16x32_bf16 v[24:27], v[238:241], v[198:201], v[24:27]
	ds_read_b128 v[186:189], v136 offset:1024
	v_mfma_f32_16x16x32_bf16 v[20:23], v[230:233], v[206:209], v[20:23]
	ds_read_b128 v[190:193], v136 offset:2048
	v_mfma_f32_16x16x32_bf16 v[16:19], v[238:241], v[206:209], v[16:19]
	ds_read_b128 v[194:197], v136 offset:3072
	v_mfma_f32_16x16x32_bf16 v[12:15], v[230:233], v[214:217], v[12:15]
	v_mfma_f32_16x16x32_bf16 v[8:11], v[238:241], v[214:217], v[8:11]
	v_mfma_f32_16x16x32_bf16 v[4:7], v[230:233], v[222:225], v[4:7]
	v_mfma_f32_16x16x32_bf16 v[0:3], v[238:241], v[222:225], v[0:3]
	v_mfma_f32_16x16x32_bf16 v[28:31], v[234:237], v[202:205], v[28:31]
	v_mfma_f32_16x16x32_bf16 v[24:27], v[242:245], v[202:205], v[24:27]
	v_mfma_f32_16x16x32_bf16 v[20:23], v[234:237], v[210:213], v[20:23]
	v_mfma_f32_16x16x32_bf16 v[16:19], v[242:245], v[210:213], v[16:19]
	v_mfma_f32_16x16x32_bf16 v[12:15], v[234:237], v[218:221], v[12:15]
	v_mfma_f32_16x16x32_bf16 v[8:11], v[242:245], v[218:221], v[8:11]
	v_mfma_f32_16x16x32_bf16 v[4:7], v[234:237], v[226:229], v[4:7]
	v_mfma_f32_16x16x32_bf16 v[0:3], v[242:245], v[226:229], v[0:3]
	s_setprio 0
	s_barrier
	s_add_u32 s54, s54, s82
	s_addc_u32 s55, s55, s83
	s_mov_b32 m0, s51
	v_lshl_add_u64 v[154:155], s[54:55], 0, v[154:155]
	ds_read_b128 v[198:201], v185 offset:32768
	ds_read_b128 v[202:205], v185 offset:33792
	ds_read_b128 v[206:209], v185 offset:34816
	ds_read_b128 v[210:213], v185 offset:35840
	ds_read_b128 v[214:217], v185 offset:36864
	ds_read_b128 v[218:221], v185 offset:37888
	ds_read_b128 v[222:225], v185 offset:38912
	ds_read_b128 v[226:229], v185 offset:39936
	global_load_lds_dwordx4 v[154:155], off
	v_lshl_add_u64 v[152:153], s[54:55], 0, v[152:153]
	s_mov_b32 m0, s8
	s_nop 0
	global_load_lds_dwordx4 v[152:153], off
	s_waitcnt lgkmcnt(8)
	s_barrier
	s_waitcnt lgkmcnt(0)
	s_setprio 1
	v_mfma_f32_16x16x32_bf16 v[124:127], v[156:159], v[198:201], v[124:127]
	v_mfma_f32_16x16x32_bf16 v[120:123], v[190:193], v[198:201], v[120:123]
	v_mfma_f32_16x16x32_bf16 v[116:119], v[156:159], v[206:209], v[116:119]
	v_mfma_f32_16x16x32_bf16 v[112:115], v[190:193], v[206:209], v[112:115]
	v_mfma_f32_16x16x32_bf16 v[108:111], v[156:159], v[214:217], v[108:111]
	v_mfma_f32_16x16x32_bf16 v[104:107], v[190:193], v[214:217], v[104:107]
	v_mfma_f32_16x16x32_bf16 v[100:103], v[156:159], v[222:225], v[100:103]
	v_mfma_f32_16x16x32_bf16 v[96:99], v[190:193], v[222:225], v[96:99]
	v_mfma_f32_16x16x32_bf16 v[124:127], v[186:189], v[202:205], v[124:127]
	v_mfma_f32_16x16x32_bf16 v[120:123], v[194:197], v[202:205], v[120:123]
	v_mfma_f32_16x16x32_bf16 v[116:119], v[186:189], v[210:213], v[116:119]
	v_mfma_f32_16x16x32_bf16 v[112:115], v[194:197], v[210:213], v[112:115]
	v_mfma_f32_16x16x32_bf16 v[108:111], v[186:189], v[218:221], v[108:111]
	v_mfma_f32_16x16x32_bf16 v[104:107], v[194:197], v[218:221], v[104:107]
	v_mfma_f32_16x16x32_bf16 v[100:103], v[186:189], v[226:229], v[100:103]
	v_mfma_f32_16x16x32_bf16 v[96:99], v[194:197], v[226:229], v[96:99]
	s_setprio 0
	s_barrier
	s_add_i32 s54, 0, 0x1c000
	s_add_i32 s55, s65, s9
	v_add_u32_e32 v136, s54, v184
	v_lshl_add_u64 v[242:243], v[246:247], 0, s[44:45]
	s_mov_b32 m0, s55
	ds_read_b128 v[152:155], v136
	ds_read_b128 v[230:233], v136 offset:1024
	ds_read_b128 v[234:237], v136 offset:2048
	ds_read_b128 v[238:241], v136 offset:3072
	global_load_lds_dwordx4 v[242:243], off
	v_lshl_add_u64 v[242:243], v[248:249], 0, s[44:45]
	s_add_i32 m0, s55, 0x2000
	s_nop 0
	global_load_lds_dwordx4 v[242:243], off
	s_barrier
; #define PG8_STAGE(bufoff, gbase, v0, v1) do { \
;         __builtin_amdgcn_global_load_lds((const unsigned*)((const char*)(gbase) + (v0)), (LAS unsigned*)(lds + (bufoff) + ldsw), 16, 0, 0); \
;         __builtin_amdgcn_global_load_lds((const unsigned*)((const char*)(gbase) + (v1)), (LAS unsigned*)(lds + (bufoff) + ldsw + 8192), 16, 0, 0); } while (0)
; #define PG8_LDA(dst, b, h) do { _Pragma("unroll") for (int m = 0; m < 4; ++m) _Pragma("unroll") for (int k = 0; k < 2; ++k) dst[m][k] = *(const LAS bf16x8*)(lds + PG8_SA(b, h) + aoff + m * 2048 + k * 1024); } while (0)
; #define PG8_MMA(ai, bj, At, Bt) do { __builtin_amdgcn_s_setprio(1); _Pragma("unroll") for (int m = 0; m < 4; ++m) _Pragma("unroll") for (int n = 0; n < 2; ++n) _Pragma("unroll") for (int k = 0; k < 2; ++k) \
;         acc[ai][bj][m][n] = __builtin_amdgcn_mfma_f32_16x16x32_bf16(Bt[n][k], At[m][k], acc[ai][bj][m][n], 0, 0, 0); __builtin_amdgcn_s_setprio(0); } while (0)
; #define PG8_WAIT_V(n) asm volatile("s_waitcnt vmcnt(" #n ")" ::: "memory")
; #define PG8_WAIT_L(n) asm volatile("s_waitcnt lgkmcnt(" #n ")" ::: "memory")
; #define PG8_BAR __builtin_amdgcn_s_barrier()
; #define PG8_SCHED __builtin_amdgcn_sched_barrier(0)
; template <class Epi, class Sched>
; __device__ __forceinline__ void gemm_phase(LAS unsigned char* lds, const Sched& S, const Epi& E) {
;     ...
;         for (int t = 0; t < nt; t += 2) {
;             const bool last = (t == nt - 2);
;             const char* a1 = cA + (size_t)(t + 1) * kstep;
;             const char* a2 = last ? nA : cA + (size_t)(t + 2) * kstep; const char* b2 = last ? nB : cB + (size_t)(t + 2) * kstep;
;             const char* a3 = a2 + kstep; const char* b3 = b2 + kstep;
;             const unsigned xA0 = last ? nvA0 : vA0, xA1 = last ? nvA1 : vA1, xB0 = last ? nvB0 : vB0, xB1 = last ? nvB1 : vB1;
;             const size_t xhA = last ? nhA : hA, xhB = last ? nhB : hB;
;     ...
;             PG8_BAR; PG8_WAIT_L(0); PG8_MMA(0, 1, At, B1); PG8_BAR;
;             PG8_LDA(At, 1, 1); PG8_STAGE(PG8_SA(1, 0), a3, xA0, xA1);
;             PG8_BAR; PG8_WAIT_L(0); PG8_MMA(1, 0, At, B0); PG8_BAR; PG8_SCHED;
;             PG8_STAGE(PG8_SB(1, 1), b3 + xhB, xB0, xB1);
;             PG8_WAIT_V(6); PG8_BAR; PG8_MMA(1, 1, At, B1); PG8_BAR;
	s_waitcnt lgkmcnt(0)
	s_setprio 1
	v_mfma_f32_16x16x32_bf16 v[92:95], v[152:155], v[198:201], v[92:95]
	v_mfma_f32_16x16x32_bf16 v[88:91], v[234:237], v[198:201], v[88:91]
	v_mfma_f32_16x16x32_bf16 v[84:87], v[152:155], v[206:209], v[84:87]
	v_mfma_f32_16x16x32_bf16 v[80:83], v[234:237], v[206:209], v[80:83]
	v_mfma_f32_16x16x32_bf16 v[76:79], v[152:155], v[214:217], v[76:79]
	v_mfma_f32_16x16x32_bf16 v[72:75], v[234:237], v[214:217], v[72:75]
	v_mfma_f32_16x16x32_bf16 v[68:71], v[152:155], v[222:225], v[68:71]
	v_mfma_f32_16x16x32_bf16 v[64:67], v[234:237], v[222:225], v[64:67]
	v_mfma_f32_16x16x32_bf16 v[92:95], v[230:233], v[202:205], v[92:95]
	v_mfma_f32_16x16x32_bf16 v[88:91], v[238:241], v[202:205], v[88:91]
	v_mfma_f32_16x16x32_bf16 v[84:87], v[230:233], v[210:213], v[84:87]
	v_mfma_f32_16x16x32_bf16 v[80:83], v[238:241], v[210:213], v[80:83]
	v_mfma_f32_16x16x32_bf16 v[76:79], v[230:233], v[218:221], v[76:79]
	v_mfma_f32_16x16x32_bf16 v[72:75], v[238:241], v[218:221], v[72:75]
	v_mfma_f32_16x16x32_bf16 v[68:71], v[230:233], v[226:229], v[68:71]
	v_mfma_f32_16x16x32_bf16 v[64:67], v[238:241], v[226:229], v[64:67]
	s_setprio 0
	s_mov_b32 m0, s21
	v_lshl_add_u64 v[242:243], v[250:251], 0, s[44:45]
	s_barrier
	ds_read_b128 v[198:201], v185 offset:49152
	ds_read_b128 v[202:205], v185 offset:50176
	ds_read_b128 v[206:209], v185 offset:51200
	ds_read_b128 v[210:213], v185 offset:52224
	ds_read_b128 v[214:217], v185 offset:53248
	ds_read_b128 v[218:221], v185 offset:54272
	ds_read_b128 v[222:225], v185 offset:55296
	ds_read_b128 v[226:229], v185 offset:56320
	global_load_lds_dwordx4 v[242:243], off
	v_lshl_add_u64 v[140:141], v[140:141], 0, s[44:45]
	s_mov_b32 m0, s24
	s_nop 0
	global_load_lds_dwordx4 v[140:141], off
	s_barrier
	s_waitcnt lgkmcnt(0)
	s_setprio 1
	v_mfma_f32_16x16x32_bf16 v[60:63], v[156:159], v[198:201], v[60:63]
	v_mfma_f32_16x16x32_bf16 v[56:59], v[190:193], v[198:201], v[56:59]
	v_mfma_f32_16x16x32_bf16 v[52:55], v[156:159], v[206:209], v[52:55]
	v_mfma_f32_16x16x32_bf16 v[48:51], v[190:193], v[206:209], v[48:51]
	v_mfma_f32_16x16x32_bf16 v[44:47], v[156:159], v[214:217], v[44:47]
	v_mfma_f32_16x16x32_bf16 v[40:43], v[190:193], v[214:217], v[40:43]
	v_mfma_f32_16x16x32_bf16 v[36:39], v[156:159], v[222:225], v[36:39]
	v_mfma_f32_16x16x32_bf16 v[32:35], v[190:193], v[222:225], v[32:35]
	v_mfma_f32_16x16x32_bf16 v[60:63], v[186:189], v[202:205], v[60:63]
	v_mfma_f32_16x16x32_bf16 v[56:59], v[194:197], v[202:205], v[56:59]
	v_mfma_f32_16x16x32_bf16 v[52:55], v[186:189], v[210:213], v[52:55]
	v_mfma_f32_16x16x32_bf16 v[48:51], v[194:197], v[210:213], v[48:51]
	v_mfma_f32_16x16x32_bf16 v[44:47], v[186:189], v[218:221], v[44:47]
	v_mfma_f32_16x16x32_bf16 v[40:43], v[194:197], v[218:221], v[40:43]
	v_mfma_f32_16x16x32_bf16 v[36:39], v[186:189], v[226:229], v[36:39]
	v_mfma_f32_16x16x32_bf16 v[32:35], v[194:197], v[226:229], v[32:35]
	s_setprio 0
	s_barrier
	s_add_i32 s54, s54, s9
	v_lshl_add_u64 v[140:141], v[160:161], 0, s[44:45]
	s_mov_b32 m0, s54
	v_lshl_add_u64 v[138:139], v[138:139], 0, s[44:45]
	global_load_lds_dwordx4 v[140:141], off
	s_add_i32 m0, s54, 0x2000
	s_nop 0
	global_load_lds_dwordx4 v[138:139], off
	s_waitcnt vmcnt(6)
	s_barrier
	s_setprio 1
	v_mfma_f32_16x16x32_bf16 v[28:31], v[152:155], v[198:201], v[28:31]
	v_mfma_f32_16x16x32_bf16 v[24:27], v[234:237], v[198:201], v[24:27]
	v_mfma_f32_16x16x32_bf16 v[20:23], v[152:155], v[206:209], v[20:23]
	v_mfma_f32_16x16x32_bf16 v[16:19], v[234:237], v[206:209], v[16:19]
	v_mfma_f32_16x16x32_bf16 v[12:15], v[152:155], v[214:217], v[12:15]
	v_mfma_f32_16x16x32_bf16 v[8:11], v[234:237], v[214:217], v[8:11]
	v_mfma_f32_16x16x32_bf16 v[4:7], v[152:155], v[222:225], v[4:7]
	v_mfma_f32_16x16x32_bf16 v[0:3], v[234:237], v[222:225], v[0:3]
	v_mfma_f32_16x16x32_bf16 v[28:31], v[230:233], v[202:205], v[28:31]
	v_mfma_f32_16x16x32_bf16 v[24:27], v[238:241], v[202:205], v[24:27]
	v_mfma_f32_16x16x32_bf16 v[20:23], v[230:233], v[210:213], v[20:23]
	v_mfma_f32_16x16x32_bf16 v[16:19], v[238:241], v[210:213], v[16:19]
	v_mfma_f32_16x16x32_bf16 v[12:15], v[230:233], v[218:221], v[12:15]
	v_mfma_f32_16x16x32_bf16 v[8:11], v[238:241], v[218:221], v[8:11]
	v_mfma_f32_16x16x32_bf16 v[4:7], v[230:233], v[226:229], v[4:7]
	v_mfma_f32_16x16x32_bf16 v[0:3], v[238:241], v[226:229], v[0:3]
	s_setprio 0
	s_add_u32 s34, s34, 0x100
	s_addc_u32 s35, s35, 0
	s_add_u32 s70, s70, 0x100
	s_addc_u32 s71, s71, 0
	s_cmp_ge_i32 s49, s36
	s_cbranch_scc1 .Lrot_exit_1
	s_cmp_eq_u32 s39, s49
	s_cselect_b64 s[54:55], -1, 0
	s_and_b64 vcc, exec, s[54:55]
	v_mov_b64_e32 v[152:153], v[144:145]
	v_mov_b64_e32 v[154:155], v[142:143]
	s_mov_b64 s[88:89], s[68:69]
	s_mov_b64 s[82:83], s[66:67]
	v_mov_b32_e32 v156, v148
	v_mov_b32_e32 v136, v146
	s_mov_b64 s[92:93], s[42:43]
	s_cbranch_vccnz .Lrot_join_1
	v_mov_b64_e32 v[152:153], v[128:129]
	v_mov_b64_e32 v[154:155], v[132:133]
	s_mov_b64 s[88:89], s[12:13]
	s_mov_b64 s[82:83], s[14:15]
	v_mov_b32_e32 v156, v130
	v_mov_b32_e32 v136, v131
	s_mov_b64 s[92:93], s[70:71]

; #define PG8_STAGE(bufoff, gbase, v0, v1) do { \
;         __builtin_amdgcn_global_load_lds((const unsigned*)((const char*)(gbase) + (v0)), (LAS unsigned*)(lds + (bufoff) + ldsw), 16, 0, 0); \
;         __builtin_amdgcn_global_load_lds((const unsigned*)((const char*)(gbase) + (v1)), (LAS unsigned*)(lds + (bufoff) + ldsw + 8192), 16, 0, 0); } while (0)
; #define PG8_LDA(dst, b, h) do { _Pragma("unroll") for (int m = 0; m < 4; ++m) _Pragma("unroll") for (int k = 0; k < 2; ++k) dst[m][k] = *(const LAS bf16x8*)(lds + PG8_SA(b, h) + aoff + m * 2048 + k * 1024); } while (0)
; #define PG8_LDB(dst, b, h) do { _Pragma("unroll") for (int n = 0; n < 2; ++n) _Pragma("unroll") for (int k = 0; k < 2; ++k) dst[n][k] = *(const LAS bf16x8*)(lds + PG8_SB(b, h) + boff + n * 2048 + k * 1024); } while (0)
; #define PG8_MMA(ai, bj, At, Bt) do { __builtin_amdgcn_s_setprio(1); _Pragma("unroll") for (int m = 0; m < 4; ++m) _Pragma("unroll") for (int n = 0; n < 2; ++n) _Pragma("unroll") for (int k = 0; k < 2; ++k) \
;         acc[ai][bj][m][n] = __builtin_amdgcn_mfma_f32_16x16x32_bf16(Bt[n][k], At[m][k], acc[ai][bj][m][n], 0, 0, 0); __builtin_amdgcn_s_setprio(0); } while (0)
; #define PG8_WAIT_L(n) asm volatile("s_waitcnt lgkmcnt(" #n ")" ::: "memory")
; #define PG8_BAR __builtin_amdgcn_s_barrier()
; template <class Epi, class Sched>
; __device__ __forceinline__ void gemm_phase(LAS unsigned char* lds, const Sched& S, const Epi& E) {
;     ...
;             const char* a1 = cA + (size_t)(t + 1) * kstep;
;             const char* a2 = last ? nA : cA + (size_t)(t + 2) * kstep; const char* b2 = last ? nB : cB + (size_t)(t + 2) * kstep;
;             const char* a3 = a2 + kstep; const char* b3 = b2 + kstep;
;             const unsigned xA0 = last ? nvA0 : vA0, xA1 = last ? nvA1 : vA1, xB0 = last ? nvB0 : vB0, xB1 = last ? nvB1 : vB1;
;             const size_t xhA = last ? nhA : hA, xhB = last ? nhB : hB;
;             PG8_LDB(B0, 0, 0); PG8_SCHED; PG8_LDA(At, 0, 0); PG8_STAGE(PG8_SA(1, 1), a1 + hA, vA0, vA1);
;             PG8_WAIT_L(8); PG8_BAR; PG8_WAIT_L(0); PG8_MMA(0, 0, At, B0); PG8_BAR; PG8_SCHED;
;             PG8_LDB(B1, 0, 1); PG8_STAGE(PG8_SB(0, 0), b2, xB0, xB1);
;             PG8_BAR; PG8_WAIT_L(0); PG8_MMA(0, 1, At, B1); PG8_BAR;
;             PG8_LDA(At, 0, 1); PG8_STAGE(PG8_SA(0, 0), a2, xA0, xA1);
;             PG8_BAR; PG8_WAIT_L(0); PG8_MMA(1, 0, At, B0); PG8_BAR; PG8_SCHED;
.LBB0_745:
	s_add_u32 s23, s34, 0xfff80080
	s_addc_u32 s71, s35, -1
	s_and_b64 s[42:43], exec, s[42:43]
	s_cselect_b32 s43, s25, s71
	s_cselect_b32 s42, s24, s23
	s_add_i32 s23, 0, 0x10000
	v_add_u32_e32 v138, s23, v147
	ds_read_b128 v[150:153], v138
	ds_read_b128 v[154:157], v138 offset:1024
	ds_read_b128 v[158:161], v138 offset:2048
	ds_read_b128 v[182:185], v138 offset:3072
	v_lshl_add_u64 v[138:139], s[34:35], 0, v[136:137]
	s_add_i32 m0, s50, 0xc000
	ds_read_b128 v[186:189], v148
	ds_read_b128 v[190:193], v148 offset:1024
	ds_read_b128 v[194:197], v148 offset:2048
	ds_read_b128 v[198:201], v148 offset:3072
	ds_read_b128 v[202:205], v148 offset:4096
	ds_read_b128 v[206:209], v148 offset:5120
	ds_read_b128 v[210:213], v148 offset:6144
	ds_read_b128 v[214:217], v148 offset:7168
	global_load_lds_dwordx4 v[138:139], off
	v_lshl_add_u64 v[138:139], s[34:35], 0, v[132:133]
	s_add_i32 m0, s50, 0xe000
	s_nop 0
	global_load_lds_dwordx4 v[138:139], off
	s_waitcnt lgkmcnt(8)
	s_barrier
	s_waitcnt lgkmcnt(0)
	s_setprio 1
	v_mfma_f32_16x16x32_bf16 v[124:127], v[150:153], v[186:189], v[124:127]
	v_mfma_f32_16x16x32_bf16 v[120:123], v[158:161], v[186:189], v[120:123]
	v_mfma_f32_16x16x32_bf16 v[108:111], v[150:153], v[194:197], v[108:111]
	v_mfma_f32_16x16x32_bf16 v[104:107], v[158:161], v[194:197], v[104:107]
	v_mfma_f32_16x16x32_bf16 v[92:95], v[150:153], v[202:205], v[92:95]
	v_mfma_f32_16x16x32_bf16 v[88:91], v[158:161], v[202:205], v[88:91]
	v_mfma_f32_16x16x32_bf16 v[76:79], v[150:153], v[210:213], v[76:79]
	v_mfma_f32_16x16x32_bf16 v[72:75], v[158:161], v[210:213], v[72:75]
	v_mfma_f32_16x16x32_bf16 v[124:127], v[154:157], v[190:193], v[124:127]
	v_mfma_f32_16x16x32_bf16 v[120:123], v[182:185], v[190:193], v[120:123]
	v_mfma_f32_16x16x32_bf16 v[108:111], v[154:157], v[198:201], v[108:111]
	v_mfma_f32_16x16x32_bf16 v[104:107], v[182:185], v[198:201], v[104:107]
	v_mfma_f32_16x16x32_bf16 v[92:95], v[154:157], v[206:209], v[92:95]
	v_mfma_f32_16x16x32_bf16 v[88:91], v[182:185], v[206:209], v[88:91]
	v_mfma_f32_16x16x32_bf16 v[76:79], v[154:157], v[214:217], v[76:79]
	v_mfma_f32_16x16x32_bf16 v[72:75], v[182:185], v[214:217], v[72:75]
	s_setprio 0
	s_barrier
	s_add_i32 s71, 0, 0x14000
	v_add_u32_e32 v138, s71, v147
	s_add_i32 s23, s23, s49
	ds_read_b128 v[218:221], v138
	ds_read_b128 v[222:225], v138 offset:1024
	ds_read_b128 v[226:229], v138 offset:2048
	ds_read_b128 v[230:233], v138 offset:3072
	v_lshl_add_u64 v[138:139], s[40:41], 0, v[142:143]
	s_mov_b32 m0, s23
	v_lshl_add_u64 v[140:141], s[40:41], 0, v[134:135]
	global_load_lds_dwordx4 v[138:139], off
	s_add_i32 m0, s23, 0x2000
	s_nop 0
	global_load_lds_dwordx4 v[140:141], off
	s_barrier
	s_waitcnt lgkmcnt(0)
	s_setprio 1
	v_mfma_f32_16x16x32_bf16 v[116:119], v[218:221], v[186:189], v[116:119]
	v_mfma_f32_16x16x32_bf16 v[112:115], v[226:229], v[186:189], v[112:115]
	v_mfma_f32_16x16x32_bf16 v[100:103], v[218:221], v[194:197], v[100:103]
	v_mfma_f32_16x16x32_bf16 v[96:99], v[226:229], v[194:197], v[96:99]
	v_mfma_f32_16x16x32_bf16 v[84:87], v[218:221], v[202:205], v[84:87]
	v_mfma_f32_16x16x32_bf16 v[80:83], v[226:229], v[202:205], v[80:83]
	v_mfma_f32_16x16x32_bf16 v[68:71], v[218:221], v[210:213], v[68:71]
	v_mfma_f32_16x16x32_bf16 v[64:67], v[226:229], v[210:213], v[64:67]
	v_mfma_f32_16x16x32_bf16 v[116:119], v[222:225], v[190:193], v[116:119]
	v_mfma_f32_16x16x32_bf16 v[112:115], v[230:233], v[190:193], v[112:115]
	v_mfma_f32_16x16x32_bf16 v[100:103], v[222:225], v[198:201], v[100:103]
	v_mfma_f32_16x16x32_bf16 v[96:99], v[230:233], v[198:201], v[96:99]
	v_mfma_f32_16x16x32_bf16 v[84:87], v[222:225], v[206:209], v[84:87]
	v_mfma_f32_16x16x32_bf16 v[80:83], v[230:233], v[206:209], v[80:83]
	v_mfma_f32_16x16x32_bf16 v[68:71], v[222:225], v[214:217], v[68:71]
	v_mfma_f32_16x16x32_bf16 v[64:67], v[230:233], v[214:217], v[64:67]
	s_setprio 0
	s_mov_b32 m0, s50
	v_lshl_add_u64 v[234:235], s[42:43], 0, v[142:143]
	s_barrier
	ds_read_b128 v[186:189], v148 offset:16384
	ds_read_b128 v[190:193], v148 offset:17408
	ds_read_b128 v[194:197], v148 offset:18432
	ds_read_b128 v[198:201], v148 offset:19456
	ds_read_b128 v[202:205], v148 offset:20480
	ds_read_b128 v[206:209], v148 offset:21504
	ds_read_b128 v[210:213], v148 offset:22528
	ds_read_b128 v[214:217], v148 offset:23552
	global_load_lds_dwordx4 v[234:235], off
	v_lshl_add_u64 v[236:237], s[42:43], 0, v[134:135]
	s_mov_b32 m0, s51
	s_nop 0
	global_load_lds_dwordx4 v[236:237], off
	s_barrier
	s_waitcnt lgkmcnt(0)
	s_setprio 1
	v_mfma_f32_16x16x32_bf16 v[60:63], v[150:153], v[186:189], v[60:63]
	v_mfma_f32_16x16x32_bf16 v[56:59], v[158:161], v[186:189], v[56:59]
	v_mfma_f32_16x16x32_bf16 v[44:47], v[150:153], v[194:197], v[44:47]
	v_mfma_f32_16x16x32_bf16 v[40:43], v[158:161], v[194:197], v[40:43]
	v_mfma_f32_16x16x32_bf16 v[28:31], v[150:153], v[202:205], v[28:31]
	v_mfma_f32_16x16x32_bf16 v[24:27], v[158:161], v[202:205], v[24:27]
	v_mfma_f32_16x16x32_bf16 v[12:15], v[150:153], v[210:213], v[12:15]
	v_mfma_f32_16x16x32_bf16 v[8:11], v[158:161], v[210:213], v[8:11]
	v_mfma_f32_16x16x32_bf16 v[60:63], v[154:157], v[190:193], v[60:63]
	v_mfma_f32_16x16x32_bf16 v[56:59], v[182:185], v[190:193], v[56:59]
	v_mfma_f32_16x16x32_bf16 v[44:47], v[154:157], v[198:201], v[44:47]
	v_mfma_f32_16x16x32_bf16 v[40:43], v[182:185], v[198:201], v[40:43]
	v_mfma_f32_16x16x32_bf16 v[28:31], v[154:157], v[206:209], v[28:31]
	v_mfma_f32_16x16x32_bf16 v[24:27], v[182:185], v[206:209], v[24:27]
	v_mfma_f32_16x16x32_bf16 v[12:15], v[154:157], v[214:217], v[12:15]
	v_mfma_f32_16x16x32_bf16 v[8:11], v[182:185], v[214:217], v[8:11]
	s_setprio 0
	s_barrier
; #define PG8_STAGE(bufoff, gbase, v0, v1) do { \
;         __builtin_amdgcn_global_load_lds((const unsigned*)((const char*)(gbase) + (v0)), (LAS unsigned*)(lds + (bufoff) + ldsw), 16, 0, 0); \
;         __builtin_amdgcn_global_load_lds((const unsigned*)((const char*)(gbase) + (v1)), (LAS unsigned*)(lds + (bufoff) + ldsw + 8192), 16, 0, 0); } while (0)
; #define PG8_LDA(dst, b, h) do { _Pragma("unroll") for (int m = 0; m < 4; ++m) _Pragma("unroll") for (int k = 0; k < 2; ++k) dst[m][k] = *(const LAS bf16x8*)(lds + PG8_SA(b, h) + aoff + m * 2048 + k * 1024); } while (0)
; #define PG8_LDB(dst, b, h) do { _Pragma("unroll") for (int n = 0; n < 2; ++n) _Pragma("unroll") for (int k = 0; k < 2; ++k) dst[n][k] = *(const LAS bf16x8*)(lds + PG8_SB(b, h) + boff + n * 2048 + k * 1024); } while (0)
; #define PG8_MMA(ai, bj, At, Bt) do { __builtin_amdgcn_s_setprio(1); _Pragma("unroll") for (int m = 0; m < 4; ++m) _Pragma("unroll") for (int n = 0; n < 2; ++n) _Pragma("unroll") for (int k = 0; k < 2; ++k) \
;         acc[ai][bj][m][n] = __builtin_amdgcn_mfma_f32_16x16x32_bf16(Bt[n][k], At[m][k], acc[ai][bj][m][n], 0, 0, 0); __builtin_amdgcn_s_setprio(0); } while (0)
; #define PG8_WAIT_V(n) asm volatile("s_waitcnt vmcnt(" #n ")" ::: "memory")
; #define PG8_WAIT_L(n) asm volatile("s_waitcnt lgkmcnt(" #n ")" ::: "memory")
; #define PG8_BAR __builtin_amdgcn_s_barrier()
; #define PG8_SCHED __builtin_amdgcn_sched_barrier(0)
; template <class Epi, class Sched>
; __device__ __forceinline__ void gemm_phase(LAS unsigned char* lds, const Sched& S, const Epi& E) {
;     ...
;             PG8_STAGE(PG8_SB(0, 1), b2 + xhB, xB0, xB1);
;             PG8_WAIT_V(6); PG8_BAR; PG8_MMA(1, 1, At, B1); PG8_BAR;
;             PG8_LDB(B0, 1, 0); PG8_SCHED; PG8_LDA(At, 1, 0); PG8_STAGE(PG8_SA(0, 1), a2 + xhA, xA0, xA1);
;             PG8_WAIT_L(8); PG8_BAR; PG8_WAIT_L(0); PG8_MMA(0, 0, At, B0); PG8_BAR; PG8_SCHED;
;             PG8_LDB(B1, 1, 1); PG8_STAGE(PG8_SB(1, 0), b3, xB0, xB1);
	s_add_u32 s82, s40, 0x80000
	s_addc_u32 s83, s41, 0
	s_add_i32 s23, s71, s49
	v_lshl_add_u64 v[150:151], s[82:83], 0, v[142:143]
	s_mov_b32 m0, s23
	s_nop 0
	global_load_lds_dwordx4 v[150:151], off
	v_lshl_add_u64 v[150:151], s[82:83], 0, v[134:135]
	s_add_i32 m0, s23, 0x2000
	s_nop 0
	global_load_lds_dwordx4 v[150:151], off
	s_add_i32 s23, 0, 0x18000
	v_add_u32_e32 v149, s23, v147
	s_waitcnt vmcnt(6)
	s_barrier
	s_setprio 1
	v_mfma_f32_16x16x32_bf16 v[52:55], v[218:221], v[186:189], v[52:55]
	ds_read_b128 v[150:153], v149
	v_mfma_f32_16x16x32_bf16 v[48:51], v[226:229], v[186:189], v[48:51]
	ds_read_b128 v[154:157], v149 offset:1024
	v_mfma_f32_16x16x32_bf16 v[36:39], v[218:221], v[194:197], v[36:39]
	ds_read_b128 v[158:161], v149 offset:2048
	v_mfma_f32_16x16x32_bf16 v[32:35], v[226:229], v[194:197], v[32:35]
	ds_read_b128 v[182:185], v149 offset:3072
	v_mfma_f32_16x16x32_bf16 v[20:23], v[218:221], v[202:205], v[20:23]
	v_mfma_f32_16x16x32_bf16 v[16:19], v[226:229], v[202:205], v[16:19]
	v_mfma_f32_16x16x32_bf16 v[4:7], v[218:221], v[210:213], v[4:7]
	v_mfma_f32_16x16x32_bf16 v[0:3], v[226:229], v[210:213], v[0:3]
	v_mfma_f32_16x16x32_bf16 v[52:55], v[222:225], v[190:193], v[52:55]
	v_mfma_f32_16x16x32_bf16 v[48:51], v[230:233], v[190:193], v[48:51]
	v_mfma_f32_16x16x32_bf16 v[36:39], v[222:225], v[198:201], v[36:39]
	v_mfma_f32_16x16x32_bf16 v[32:35], v[230:233], v[198:201], v[32:35]
	v_mfma_f32_16x16x32_bf16 v[20:23], v[222:225], v[206:209], v[20:23]
	v_mfma_f32_16x16x32_bf16 v[16:19], v[230:233], v[206:209], v[16:19]
	v_mfma_f32_16x16x32_bf16 v[4:7], v[222:225], v[214:217], v[4:7]
	v_mfma_f32_16x16x32_bf16 v[0:3], v[230:233], v[214:217], v[0:3]
	s_setprio 0
	s_barrier
	s_add_u32 s42, s42, 0x80000
	s_addc_u32 s43, s43, 0
	s_mov_b32 m0, s54
	v_lshl_add_u64 v[218:219], s[42:43], 0, v[142:143]
	ds_read_b128 v[186:189], v148 offset:32768
	ds_read_b128 v[190:193], v148 offset:33792
	ds_read_b128 v[194:197], v148 offset:34816
	ds_read_b128 v[198:201], v148 offset:35840
	ds_read_b128 v[202:205], v148 offset:36864
	ds_read_b128 v[206:209], v148 offset:37888
	ds_read_b128 v[210:213], v148 offset:38912
	ds_read_b128 v[214:217], v148 offset:39936
	global_load_lds_dwordx4 v[218:219], off
	v_lshl_add_u64 v[218:219], s[42:43], 0, v[134:135]
	s_mov_b32 m0, s55
	s_nop 0
	global_load_lds_dwordx4 v[218:219], off
	s_waitcnt lgkmcnt(8)
	s_barrier
	s_waitcnt lgkmcnt(0)
	s_setprio 1
	v_mfma_f32_16x16x32_bf16 v[124:127], v[150:153], v[186:189], v[124:127]
	v_mfma_f32_16x16x32_bf16 v[120:123], v[158:161], v[186:189], v[120:123]
	v_mfma_f32_16x16x32_bf16 v[108:111], v[150:153], v[194:197], v[108:111]
	v_mfma_f32_16x16x32_bf16 v[104:107], v[158:161], v[194:197], v[104:107]
	v_mfma_f32_16x16x32_bf16 v[92:95], v[150:153], v[202:205], v[92:95]
	v_mfma_f32_16x16x32_bf16 v[88:91], v[158:161], v[202:205], v[88:91]
	v_mfma_f32_16x16x32_bf16 v[76:79], v[150:153], v[210:213], v[76:79]
	v_mfma_f32_16x16x32_bf16 v[72:75], v[158:161], v[210:213], v[72:75]
	v_mfma_f32_16x16x32_bf16 v[124:127], v[154:157], v[190:193], v[124:127]
	v_mfma_f32_16x16x32_bf16 v[120:123], v[182:185], v[190:193], v[120:123]
	v_mfma_f32_16x16x32_bf16 v[108:111], v[154:157], v[198:201], v[108:111]
	v_mfma_f32_16x16x32_bf16 v[104:107], v[182:185], v[198:201], v[104:107]
	v_mfma_f32_16x16x32_bf16 v[92:95], v[154:157], v[206:209], v[92:95]
	v_mfma_f32_16x16x32_bf16 v[88:91], v[182:185], v[206:209], v[88:91]
	v_mfma_f32_16x16x32_bf16 v[76:79], v[154:157], v[214:217], v[76:79]
	v_mfma_f32_16x16x32_bf16 v[72:75], v[182:185], v[214:217], v[72:75]
	s_setprio 0
	s_barrier
	s_add_i32 s42, 0, 0x1c000
	s_add_i32 s23, s23, s49
	v_add_u32_e32 v149, s42, v147
	v_lshl_add_u64 v[138:139], v[138:139], 0, s[44:45]
	s_mov_b32 m0, s23
	ds_read_b128 v[218:221], v149
	ds_read_b128 v[222:225], v149 offset:1024
	ds_read_b128 v[226:229], v149 offset:2048
	ds_read_b128 v[230:233], v149 offset:3072
	global_load_lds_dwordx4 v[138:139], off
	v_lshl_add_u64 v[138:139], v[140:141], 0, s[44:45]
	s_add_i32 m0, s23, 0x2000
	s_nop 0
	global_load_lds_dwordx4 v[138:139], off
	s_barrier
; #define PG8_STAGE(bufoff, gbase, v0, v1) do { \
;         __builtin_amdgcn_global_load_lds((const unsigned*)((const char*)(gbase) + (v0)), (LAS unsigned*)(lds + (bufoff) + ldsw), 16, 0, 0); \
;         __builtin_amdgcn_global_load_lds((const unsigned*)((const char*)(gbase) + (v1)), (LAS unsigned*)(lds + (bufoff) + ldsw + 8192), 16, 0, 0); } while (0)
; #define PG8_LDA(dst, b, h) do { _Pragma("unroll") for (int m = 0; m < 4; ++m) _Pragma("unroll") for (int k = 0; k < 2; ++k) dst[m][k] = *(const LAS bf16x8*)(lds + PG8_SA(b, h) + aoff + m * 2048 + k * 1024); } while (0)
; #define PG8_MMA(ai, bj, At, Bt) do { __builtin_amdgcn_s_setprio(1); _Pragma("unroll") for (int m = 0; m < 4; ++m) _Pragma("unroll") for (int n = 0; n < 2; ++n) _Pragma("unroll") for (int k = 0; k < 2; ++k) \
;         acc[ai][bj][m][n] = __builtin_amdgcn_mfma_f32_16x16x32_bf16(Bt[n][k], At[m][k], acc[ai][bj][m][n], 0, 0, 0); __builtin_amdgcn_s_setprio(0); } while (0)
; #define PG8_WAIT_V(n) asm volatile("s_waitcnt vmcnt(" #n ")" ::: "memory")
; #define PG8_WAIT_L(n) asm volatile("s_waitcnt lgkmcnt(" #n ")" ::: "memory")
; #define PG8_BAR __builtin_amdgcn_s_barrier()
; #define PG8_SCHED __builtin_amdgcn_sched_barrier(0)
; template <class Epi, class Sched>
; __device__ __forceinline__ void gemm_phase(LAS unsigned char* lds, const Sched& S, const Epi& E) {
;     ...
;         for (int t = 0; t < nt; t += 2) {
;             const bool last = (t == nt - 2);
;             const char* a1 = cA + (size_t)(t + 1) * kstep;
;             const char* a2 = last ? nA : cA + (size_t)(t + 2) * kstep; const char* b2 = last ? nB : cB + (size_t)(t + 2) * kstep;
;             const char* a3 = a2 + kstep; const char* b3 = b2 + kstep;
;             const unsigned xA0 = last ? nvA0 : vA0, xA1 = last ? nvA1 : vA1, xB0 = last ? nvB0 : vB0, xB1 = last ? nvB1 : vB1;
;             const size_t xhA = last ? nhA : hA, xhB = last ? nhB : hB;
;     ...
;             PG8_BAR; PG8_WAIT_L(0); PG8_MMA(0, 1, At, B1); PG8_BAR;
;             PG8_LDA(At, 1, 1); PG8_STAGE(PG8_SA(1, 0), a3, xA0, xA1);
;             PG8_BAR; PG8_WAIT_L(0); PG8_MMA(1, 0, At, B0); PG8_BAR; PG8_SCHED;
;             PG8_STAGE(PG8_SB(1, 1), b3 + xhB, xB0, xB1);
;             PG8_WAIT_V(6); PG8_BAR; PG8_MMA(1, 1, At, B1); PG8_BAR;
	s_waitcnt lgkmcnt(0)
	s_setprio 1
	v_mfma_f32_16x16x32_bf16 v[116:119], v[218:221], v[186:189], v[116:119]
	v_mfma_f32_16x16x32_bf16 v[112:115], v[226:229], v[186:189], v[112:115]
	v_mfma_f32_16x16x32_bf16 v[100:103], v[218:221], v[194:197], v[100:103]
	v_mfma_f32_16x16x32_bf16 v[96:99], v[226:229], v[194:197], v[96:99]
	v_mfma_f32_16x16x32_bf16 v[84:87], v[218:221], v[202:205], v[84:87]
	v_mfma_f32_16x16x32_bf16 v[80:83], v[226:229], v[202:205], v[80:83]
	v_mfma_f32_16x16x32_bf16 v[68:71], v[218:221], v[210:213], v[68:71]
	v_mfma_f32_16x16x32_bf16 v[64:67], v[226:229], v[210:213], v[64:67]
	v_mfma_f32_16x16x32_bf16 v[116:119], v[222:225], v[190:193], v[116:119]
	v_mfma_f32_16x16x32_bf16 v[112:115], v[230:233], v[190:193], v[112:115]
	v_mfma_f32_16x16x32_bf16 v[100:103], v[222:225], v[198:201], v[100:103]
	v_mfma_f32_16x16x32_bf16 v[96:99], v[230:233], v[198:201], v[96:99]
	v_mfma_f32_16x16x32_bf16 v[84:87], v[222:225], v[206:209], v[84:87]
	v_mfma_f32_16x16x32_bf16 v[80:83], v[230:233], v[206:209], v[80:83]
	v_mfma_f32_16x16x32_bf16 v[68:71], v[222:225], v[214:217], v[68:71]
	v_mfma_f32_16x16x32_bf16 v[64:67], v[230:233], v[214:217], v[64:67]
	s_setprio 0
	s_mov_b32 m0, s66
	v_lshl_add_u64 v[138:139], v[234:235], 0, s[44:45]
	s_barrier
	ds_read_b128 v[186:189], v148 offset:49152
	ds_read_b128 v[190:193], v148 offset:50176
	ds_read_b128 v[194:197], v148 offset:51200
	ds_read_b128 v[198:201], v148 offset:52224
	ds_read_b128 v[202:205], v148 offset:53248
	ds_read_b128 v[206:209], v148 offset:54272
	ds_read_b128 v[210:213], v148 offset:55296
	ds_read_b128 v[214:217], v148 offset:56320
	global_load_lds_dwordx4 v[138:139], off
	v_lshl_add_u64 v[138:139], v[236:237], 0, s[44:45]
	s_mov_b32 m0, s67
	s_nop 0
	global_load_lds_dwordx4 v[138:139], off
	s_barrier
	s_waitcnt lgkmcnt(0)
	s_setprio 1
	v_mfma_f32_16x16x32_bf16 v[60:63], v[150:153], v[186:189], v[60:63]
	v_mfma_f32_16x16x32_bf16 v[56:59], v[158:161], v[186:189], v[56:59]
	v_mfma_f32_16x16x32_bf16 v[44:47], v[150:153], v[194:197], v[44:47]
	v_mfma_f32_16x16x32_bf16 v[40:43], v[158:161], v[194:197], v[40:43]
	v_mfma_f32_16x16x32_bf16 v[28:31], v[150:153], v[202:205], v[28:31]
	v_mfma_f32_16x16x32_bf16 v[24:27], v[158:161], v[202:205], v[24:27]
	v_mfma_f32_16x16x32_bf16 v[12:15], v[150:153], v[210:213], v[12:15]
	v_mfma_f32_16x16x32_bf16 v[8:11], v[158:161], v[210:213], v[8:11]
	v_mfma_f32_16x16x32_bf16 v[60:63], v[154:157], v[190:193], v[60:63]
	v_mfma_f32_16x16x32_bf16 v[56:59], v[182:185], v[190:193], v[56:59]
	v_mfma_f32_16x16x32_bf16 v[44:47], v[154:157], v[198:201], v[44:47]
	v_mfma_f32_16x16x32_bf16 v[40:43], v[182:185], v[198:201], v[40:43]
	v_mfma_f32_16x16x32_bf16 v[28:31], v[154:157], v[206:209], v[28:31]
	v_mfma_f32_16x16x32_bf16 v[24:27], v[182:185], v[206:209], v[24:27]
	v_mfma_f32_16x16x32_bf16 v[12:15], v[154:157], v[214:217], v[12:15]
	v_mfma_f32_16x16x32_bf16 v[8:11], v[182:185], v[214:217], v[8:11]
	s_setprio 0
	s_barrier
	s_add_u32 s40, s40, 0x80080
	s_addc_u32 s41, s41, 0
	s_add_i32 s23, s42, s49
	v_lshl_add_u64 v[138:139], s[40:41], 0, v[142:143]
	s_mov_b32 m0, s23
	v_lshl_add_u64 v[134:135], s[40:41], 0, v[134:135]
	global_load_lds_dwordx4 v[138:139], off
	s_add_i32 m0, s23, 0x2000
	s_nop 0
	global_load_lds_dwordx4 v[134:135], off
	s_waitcnt vmcnt(6)
	s_barrier
	s_setprio 1
	v_mfma_f32_16x16x32_bf16 v[52:55], v[218:221], v[186:189], v[52:55]
	v_mfma_f32_16x16x32_bf16 v[48:51], v[226:229], v[186:189], v[48:51]
	v_mfma_f32_16x16x32_bf16 v[36:39], v[218:221], v[194:197], v[36:39]
	v_mfma_f32_16x16x32_bf16 v[32:35], v[226:229], v[194:197], v[32:35]
	v_mfma_f32_16x16x32_bf16 v[20:23], v[218:221], v[202:205], v[20:23]
	v_mfma_f32_16x16x32_bf16 v[16:19], v[226:229], v[202:205], v[16:19]
	v_mfma_f32_16x16x32_bf16 v[4:7], v[218:221], v[210:213], v[4:7]
	v_mfma_f32_16x16x32_bf16 v[0:3], v[226:229], v[210:213], v[0:3]
	v_mfma_f32_16x16x32_bf16 v[52:55], v[222:225], v[190:193], v[52:55]
	v_mfma_f32_16x16x32_bf16 v[48:51], v[230:233], v[190:193], v[48:51]
	v_mfma_f32_16x16x32_bf16 v[36:39], v[222:225], v[198:201], v[36:39]
	v_mfma_f32_16x16x32_bf16 v[32:35], v[230:233], v[198:201], v[32:35]
	v_mfma_f32_16x16x32_bf16 v[20:23], v[222:225], v[206:209], v[20:23]
	v_mfma_f32_16x16x32_bf16 v[16:19], v[230:233], v[206:209], v[16:19]
	v_mfma_f32_16x16x32_bf16 v[4:7], v[222:225], v[214:217], v[4:7]
	v_mfma_f32_16x16x32_bf16 v[0:3], v[230:233], v[214:217], v[0:3]
	s_setprio 0
	s_add_i32 s21, s21, 2
	s_add_u32 s34, s34, 0x100
	s_addc_u32 s35, s35, 0
	s_add_u32 s38, s38, 0x100
	s_addc_u32 s39, s39, 0
	s_cmp_gt_u32 s21, 29
	s_cbranch_scc1 .Lrot_exit_2
	s_cmp_eq_u32 s21, 28
	s_cselect_b64 s[42:43], -1, 0
	s_and_b64 vcc, exec, s[42:43]
	v_mov_b64_e32 v[134:135], v[130:131]
	v_mov_b64_e32 v[142:143], v[128:129]
	s_mov_b64 s[40:41], s[26:27]
	s_cbranch_vccnz .Lrot_join_2
	v_mov_b64_e32 v[134:135], v[132:133]
	v_mov_b64_e32 v[142:143], v[136:137]
	s_mov_b64 s[40:41], s[38:39]

; #define PG8_STAGE(bufoff, gbase, v0, v1) do { \
;         __builtin_amdgcn_global_load_lds((const unsigned*)((const char*)(gbase) + (v0)), (LAS unsigned*)(lds + (bufoff) + ldsw), 16, 0, 0); \
;         __builtin_amdgcn_global_load_lds((const unsigned*)((const char*)(gbase) + (v1)), (LAS unsigned*)(lds + (bufoff) + ldsw + 8192), 16, 0, 0); } while (0)
; #define PG8_LDA(dst, b, h) do { _Pragma("unroll") for (int m = 0; m < 4; ++m) _Pragma("unroll") for (int k = 0; k < 2; ++k) dst[m][k] = *(const LAS bf16x8*)(lds + PG8_SA(b, h) + aoff + m * 2048 + k * 1024); } while (0)
; #define PG8_LDB(dst, b, h) do { _Pragma("unroll") for (int n = 0; n < 2; ++n) _Pragma("unroll") for (int k = 0; k < 2; ++k) dst[n][k] = *(const LAS bf16x8*)(lds + PG8_SB(b, h) + boff + n * 2048 + k * 1024); } while (0)
; #define PG8_MMA(ai, bj, At, Bt) do { __builtin_amdgcn_s_setprio(1); _Pragma("unroll") for (int m = 0; m < 4; ++m) _Pragma("unroll") for (int n = 0; n < 2; ++n) _Pragma("unroll") for (int k = 0; k < 2; ++k) \
;         acc[ai][bj][m][n] = __builtin_amdgcn_mfma_f32_16x16x32_bf16(Bt[n][k], At[m][k], acc[ai][bj][m][n], 0, 0, 0); __builtin_amdgcn_s_setprio(0); } while (0)
; #define PG8_WAIT_L(n) asm volatile("s_waitcnt lgkmcnt(" #n ")" ::: "memory")
; #define PG8_BAR __builtin_amdgcn_s_barrier()
; template <class Epi, class Sched>
; __device__ __forceinline__ void gemm_phase(LAS unsigned char* lds, const Sched& S, const Epi& E) {
;     ...
;             const char* a1 = cA + (size_t)(t + 1) * kstep;
;             const char* a2 = last ? nA : cA + (size_t)(t + 2) * kstep; const char* b2 = last ? nB : cB + (size_t)(t + 2) * kstep;
;             const char* a3 = a2 + kstep; const char* b3 = b2 + kstep;
;             const unsigned xA0 = last ? nvA0 : vA0, xA1 = last ? nvA1 : vA1, xB0 = last ? nvB0 : vB0, xB1 = last ? nvB1 : vB1;
;             const size_t xhA = last ? nhA : hA, xhB = last ? nhB : hB;
;             PG8_LDB(B0, 0, 0); PG8_SCHED; PG8_LDA(At, 0, 0); PG8_STAGE(PG8_SA(1, 1), a1 + hA, vA0, vA1);
;             PG8_WAIT_L(8); PG8_BAR; PG8_WAIT_L(0); PG8_MMA(0, 0, At, B0); PG8_BAR; PG8_SCHED;
;             PG8_LDB(B1, 0, 1); PG8_STAGE(PG8_SB(0, 0), b2, xB0, xB1);
;             PG8_BAR; PG8_WAIT_L(0); PG8_MMA(0, 1, At, B1); PG8_BAR;
;             PG8_LDA(At, 0, 1); PG8_STAGE(PG8_SA(0, 0), a2, xA0, xA1);
;             PG8_BAR; PG8_WAIT_L(0); PG8_MMA(1, 0, At, B0); PG8_BAR; PG8_SCHED;
.LBB0_808:
	s_add_u32 s21, s26, 0xfff80080
	s_addc_u32 s69, s27, -1
	s_and_b64 s[40:41], exec, s[40:41]
	s_cselect_b32 s41, s23, s69
	s_cselect_b32 s40, s22, s21
	s_add_i32 s21, 0, 0x10000
	v_add_u32_e32 v138, s21, v155
	ds_read_b128 v[158:161], v138
	ds_read_b128 v[182:185], v138 offset:1024
	ds_read_b128 v[186:189], v138 offset:2048
	ds_read_b128 v[190:193], v138 offset:3072
	v_lshl_add_u64 v[138:139], s[26:27], 0, v[132:133]
	s_add_i32 m0, s48, 0xc000
	ds_read_b128 v[194:197], v143
	ds_read_b128 v[198:201], v143 offset:1024
	ds_read_b128 v[202:205], v143 offset:2048
	ds_read_b128 v[206:209], v143 offset:3072
	ds_read_b128 v[210:213], v143 offset:4096
	ds_read_b128 v[214:217], v143 offset:5120
	ds_read_b128 v[218:221], v143 offset:6144
	ds_read_b128 v[222:225], v143 offset:7168
	global_load_lds_dwordx4 v[138:139], off
	v_lshl_add_u64 v[138:139], s[26:27], 0, v[134:135]
	s_add_i32 m0, s48, 0xe000
	s_nop 0
	global_load_lds_dwordx4 v[138:139], off
	s_waitcnt lgkmcnt(8)
	s_barrier
	s_waitcnt lgkmcnt(0)
	s_setprio 1
	v_mfma_f32_16x16x32_bf16 v[124:127], v[158:161], v[194:197], v[124:127]
	v_mfma_f32_16x16x32_bf16 v[120:123], v[186:189], v[194:197], v[120:123]
	v_mfma_f32_16x16x32_bf16 v[112:115], v[158:161], v[202:205], v[112:115]
	v_mfma_f32_16x16x32_bf16 v[104:107], v[186:189], v[202:205], v[104:107]
	v_mfma_f32_16x16x32_bf16 v[96:99], v[158:161], v[210:213], v[96:99]
	v_mfma_f32_16x16x32_bf16 v[88:91], v[186:189], v[210:213], v[88:91]
	v_mfma_f32_16x16x32_bf16 v[80:83], v[158:161], v[218:221], v[80:83]
	v_mfma_f32_16x16x32_bf16 v[72:75], v[186:189], v[218:221], v[72:75]
	v_mfma_f32_16x16x32_bf16 v[124:127], v[182:185], v[198:201], v[124:127]
	v_mfma_f32_16x16x32_bf16 v[120:123], v[190:193], v[198:201], v[120:123]
	v_mfma_f32_16x16x32_bf16 v[112:115], v[182:185], v[206:209], v[112:115]
	v_mfma_f32_16x16x32_bf16 v[104:107], v[190:193], v[206:209], v[104:107]
	v_mfma_f32_16x16x32_bf16 v[96:99], v[182:185], v[214:217], v[96:99]
	v_mfma_f32_16x16x32_bf16 v[88:91], v[190:193], v[214:217], v[88:91]
	v_mfma_f32_16x16x32_bf16 v[80:83], v[182:185], v[222:225], v[80:83]
	v_mfma_f32_16x16x32_bf16 v[72:75], v[190:193], v[222:225], v[72:75]
	s_setprio 0
	s_barrier
	s_add_i32 s69, 0, 0x14000
	s_add_i32 s21, s21, s43
	v_add_u32_e32 v138, s69, v155
	s_mov_b32 m0, s21
	ds_read_b128 v[226:229], v138
	ds_read_b128 v[230:233], v138 offset:1024
	ds_read_b128 v[234:237], v138 offset:2048
	ds_read_b128 v[238:241], v138 offset:3072
	global_load_lds_dwordx4 v136, s[38:39]
	s_add_i32 m0, s21, 0x2000
	v_mov_b32_e32 v147, v137
	global_load_lds_dwordx4 v146, s[38:39]
	s_barrier
	s_waitcnt lgkmcnt(0)
	v_lshl_add_u64 v[138:139], s[38:39], 0, v[136:137]
	v_lshl_add_u64 v[140:141], s[38:39], 0, v[146:147]
	s_setprio 1
	v_mfma_f32_16x16x32_bf16 v[116:119], v[226:229], v[194:197], v[116:119]
	v_mfma_f32_16x16x32_bf16 v[108:111], v[234:237], v[194:197], v[108:111]
	v_mfma_f32_16x16x32_bf16 v[100:103], v[226:229], v[202:205], v[100:103]
	v_mfma_f32_16x16x32_bf16 v[92:95], v[234:237], v[202:205], v[92:95]
	v_mfma_f32_16x16x32_bf16 v[84:87], v[226:229], v[210:213], v[84:87]
	v_mfma_f32_16x16x32_bf16 v[76:79], v[234:237], v[210:213], v[76:79]
	v_mfma_f32_16x16x32_bf16 v[68:71], v[226:229], v[218:221], v[68:71]
	v_mfma_f32_16x16x32_bf16 v[64:67], v[234:237], v[218:221], v[64:67]
	v_mfma_f32_16x16x32_bf16 v[116:119], v[230:233], v[198:201], v[116:119]
	v_mfma_f32_16x16x32_bf16 v[108:111], v[238:241], v[198:201], v[108:111]
	v_mfma_f32_16x16x32_bf16 v[100:103], v[230:233], v[206:209], v[100:103]
	v_mfma_f32_16x16x32_bf16 v[92:95], v[238:241], v[206:209], v[92:95]
	v_mfma_f32_16x16x32_bf16 v[84:87], v[230:233], v[214:217], v[84:87]
	v_mfma_f32_16x16x32_bf16 v[76:79], v[238:241], v[214:217], v[76:79]
	v_mfma_f32_16x16x32_bf16 v[68:71], v[230:233], v[222:225], v[68:71]
	v_mfma_f32_16x16x32_bf16 v[64:67], v[238:241], v[222:225], v[64:67]
	s_setprio 0
	s_mov_b32 m0, s48
	v_lshl_add_u64 v[242:243], s[40:41], 0, v[150:151]
	s_barrier
	ds_read_b128 v[194:197], v143 offset:16384
	ds_read_b128 v[198:201], v143 offset:17408
	ds_read_b128 v[202:205], v143 offset:18432
	ds_read_b128 v[206:209], v143 offset:19456
	ds_read_b128 v[210:213], v143 offset:20480
	ds_read_b128 v[214:217], v143 offset:21504
	ds_read_b128 v[218:221], v143 offset:22528
	ds_read_b128 v[222:225], v143 offset:23552
	global_load_lds_dwordx4 v[242:243], off
	v_lshl_add_u64 v[244:245], s[40:41], 0, v[148:149]
	s_mov_b32 m0, s49
	s_nop 0
	global_load_lds_dwordx4 v[244:245], off
	s_barrier
	s_waitcnt lgkmcnt(0)
	s_setprio 1
	v_mfma_f32_16x16x32_bf16 v[60:63], v[158:161], v[194:197], v[60:63]
	v_mfma_f32_16x16x32_bf16 v[56:59], v[186:189], v[194:197], v[56:59]
	v_mfma_f32_16x16x32_bf16 v[44:47], v[158:161], v[202:205], v[44:47]
	v_mfma_f32_16x16x32_bf16 v[40:43], v[186:189], v[202:205], v[40:43]
	v_mfma_f32_16x16x32_bf16 v[28:31], v[158:161], v[210:213], v[28:31]
	v_mfma_f32_16x16x32_bf16 v[24:27], v[186:189], v[210:213], v[24:27]
	v_mfma_f32_16x16x32_bf16 v[12:15], v[158:161], v[218:221], v[12:15]
	v_mfma_f32_16x16x32_bf16 v[8:11], v[186:189], v[218:221], v[8:11]
	v_mfma_f32_16x16x32_bf16 v[60:63], v[182:185], v[198:201], v[60:63]
	v_mfma_f32_16x16x32_bf16 v[56:59], v[190:193], v[198:201], v[56:59]
	v_mfma_f32_16x16x32_bf16 v[44:47], v[182:185], v[206:209], v[44:47]
	v_mfma_f32_16x16x32_bf16 v[40:43], v[190:193], v[206:209], v[40:43]
	v_mfma_f32_16x16x32_bf16 v[28:31], v[182:185], v[214:217], v[28:31]
	v_mfma_f32_16x16x32_bf16 v[24:27], v[190:193], v[214:217], v[24:27]
	v_mfma_f32_16x16x32_bf16 v[12:15], v[182:185], v[222:225], v[12:15]
	v_mfma_f32_16x16x32_bf16 v[8:11], v[190:193], v[222:225], v[8:11]
	s_setprio 0
	s_barrier
; #define PG8_STAGE(bufoff, gbase, v0, v1) do { \
;         __builtin_amdgcn_global_load_lds((const unsigned*)((const char*)(gbase) + (v0)), (LAS unsigned*)(lds + (bufoff) + ldsw), 16, 0, 0); \
;         __builtin_amdgcn_global_load_lds((const unsigned*)((const char*)(gbase) + (v1)), (LAS unsigned*)(lds + (bufoff) + ldsw + 8192), 16, 0, 0); } while (0)
; #define PG8_LDA(dst, b, h) do { _Pragma("unroll") for (int m = 0; m < 4; ++m) _Pragma("unroll") for (int k = 0; k < 2; ++k) dst[m][k] = *(const LAS bf16x8*)(lds + PG8_SA(b, h) + aoff + m * 2048 + k * 1024); } while (0)
; #define PG8_LDB(dst, b, h) do { _Pragma("unroll") for (int n = 0; n < 2; ++n) _Pragma("unroll") for (int k = 0; k < 2; ++k) dst[n][k] = *(const LAS bf16x8*)(lds + PG8_SB(b, h) + boff + n * 2048 + k * 1024); } while (0)
; #define PG8_MMA(ai, bj, At, Bt) do { __builtin_amdgcn_s_setprio(1); _Pragma("unroll") for (int m = 0; m < 4; ++m) _Pragma("unroll") for (int n = 0; n < 2; ++n) _Pragma("unroll") for (int k = 0; k < 2; ++k) \
;         acc[ai][bj][m][n] = __builtin_amdgcn_mfma_f32_16x16x32_bf16(Bt[n][k], At[m][k], acc[ai][bj][m][n], 0, 0, 0); __builtin_amdgcn_s_setprio(0); } while (0)
; #define PG8_WAIT_V(n) asm volatile("s_waitcnt vmcnt(" #n ")" ::: "memory")
; #define PG8_WAIT_L(n) asm volatile("s_waitcnt lgkmcnt(" #n ")" ::: "memory")
; #define PG8_BAR __builtin_amdgcn_s_barrier()
; #define PG8_SCHED __builtin_amdgcn_sched_barrier(0)
; template <class Epi, class Sched>
; __device__ __forceinline__ void gemm_phase(LAS unsigned char* lds, const Sched& S, const Epi& E) {
;     ...
;             PG8_STAGE(PG8_SB(0, 1), b2 + xhB, xB0, xB1);
;             PG8_WAIT_V(6); PG8_BAR; PG8_MMA(1, 1, At, B1); PG8_BAR;
;             PG8_LDB(B0, 1, 0); PG8_SCHED; PG8_LDA(At, 1, 0); PG8_STAGE(PG8_SA(0, 1), a2 + xhA, xA0, xA1);
;             PG8_WAIT_L(8); PG8_BAR; PG8_WAIT_L(0); PG8_MMA(0, 0, At, B0); PG8_BAR; PG8_SCHED;
;             PG8_LDB(B1, 1, 1); PG8_STAGE(PG8_SB(1, 0), b3, xB0, xB1);
	s_add_u32 s70, s38, 0x80000
	s_addc_u32 s71, s39, 0
	s_add_i32 s21, s69, s43
	s_mov_b32 m0, s21
	s_nop 0
	global_load_lds_dwordx4 v136, s[70:71]
	s_add_i32 m0, s21, 0x2000
	s_nop 0
	global_load_lds_dwordx4 v146, s[70:71]
	s_add_i32 s21, 0, 0x18000
	v_add_u32_e32 v147, s21, v155
	s_waitcnt vmcnt(6)
	s_barrier
	s_setprio 1
	v_mfma_f32_16x16x32_bf16 v[52:55], v[226:229], v[194:197], v[52:55]
	ds_read_b128 v[158:161], v147
	v_mfma_f32_16x16x32_bf16 v[48:51], v[234:237], v[194:197], v[48:51]
	ds_read_b128 v[182:185], v147 offset:1024
	v_mfma_f32_16x16x32_bf16 v[36:39], v[226:229], v[202:205], v[36:39]
	ds_read_b128 v[186:189], v147 offset:2048
	v_mfma_f32_16x16x32_bf16 v[32:35], v[234:237], v[202:205], v[32:35]
	ds_read_b128 v[190:193], v147 offset:3072
	v_mfma_f32_16x16x32_bf16 v[20:23], v[226:229], v[210:213], v[20:23]
	v_mfma_f32_16x16x32_bf16 v[16:19], v[234:237], v[210:213], v[16:19]
	v_mfma_f32_16x16x32_bf16 v[4:7], v[226:229], v[218:221], v[4:7]
	v_mfma_f32_16x16x32_bf16 v[0:3], v[234:237], v[218:221], v[0:3]
	v_mfma_f32_16x16x32_bf16 v[52:55], v[230:233], v[198:201], v[52:55]
	v_mfma_f32_16x16x32_bf16 v[48:51], v[238:241], v[198:201], v[48:51]
	v_mfma_f32_16x16x32_bf16 v[36:39], v[230:233], v[206:209], v[36:39]
	v_mfma_f32_16x16x32_bf16 v[32:35], v[238:241], v[206:209], v[32:35]
	v_mfma_f32_16x16x32_bf16 v[20:23], v[230:233], v[214:217], v[20:23]
	v_mfma_f32_16x16x32_bf16 v[16:19], v[238:241], v[214:217], v[16:19]
	v_mfma_f32_16x16x32_bf16 v[4:7], v[230:233], v[222:225], v[4:7]
	v_mfma_f32_16x16x32_bf16 v[0:3], v[238:241], v[222:225], v[0:3]
	s_setprio 0
	s_barrier
	s_add_u32 s40, s40, 0x80000
	s_addc_u32 s41, s41, 0
	s_mov_b32 m0, s50
	v_lshl_add_u64 v[150:151], s[40:41], 0, v[150:151]
	ds_read_b128 v[194:197], v143 offset:32768
	ds_read_b128 v[198:201], v143 offset:33792
	ds_read_b128 v[202:205], v143 offset:34816
	ds_read_b128 v[206:209], v143 offset:35840
	ds_read_b128 v[210:213], v143 offset:36864
	ds_read_b128 v[214:217], v143 offset:37888
	ds_read_b128 v[218:221], v143 offset:38912
	ds_read_b128 v[222:225], v143 offset:39936
	global_load_lds_dwordx4 v[150:151], off
	v_lshl_add_u64 v[148:149], s[40:41], 0, v[148:149]
	s_mov_b32 m0, s51
	s_nop 0
	global_load_lds_dwordx4 v[148:149], off
	s_waitcnt lgkmcnt(8)
	s_barrier
	s_waitcnt lgkmcnt(0)
	s_setprio 1
	v_mfma_f32_16x16x32_bf16 v[124:127], v[158:161], v[194:197], v[124:127]
	v_mfma_f32_16x16x32_bf16 v[120:123], v[186:189], v[194:197], v[120:123]
	v_mfma_f32_16x16x32_bf16 v[112:115], v[158:161], v[202:205], v[112:115]
	v_mfma_f32_16x16x32_bf16 v[104:107], v[186:189], v[202:205], v[104:107]
	v_mfma_f32_16x16x32_bf16 v[96:99], v[158:161], v[210:213], v[96:99]
	v_mfma_f32_16x16x32_bf16 v[88:91], v[186:189], v[210:213], v[88:91]
	v_mfma_f32_16x16x32_bf16 v[80:83], v[158:161], v[218:221], v[80:83]
	v_mfma_f32_16x16x32_bf16 v[72:75], v[186:189], v[218:221], v[72:75]
	v_mfma_f32_16x16x32_bf16 v[124:127], v[182:185], v[198:201], v[124:127]
	v_mfma_f32_16x16x32_bf16 v[120:123], v[190:193], v[198:201], v[120:123]
	v_mfma_f32_16x16x32_bf16 v[112:115], v[182:185], v[206:209], v[112:115]
	v_mfma_f32_16x16x32_bf16 v[104:107], v[190:193], v[206:209], v[104:107]
	v_mfma_f32_16x16x32_bf16 v[96:99], v[182:185], v[214:217], v[96:99]
	v_mfma_f32_16x16x32_bf16 v[88:91], v[190:193], v[214:217], v[88:91]
	v_mfma_f32_16x16x32_bf16 v[80:83], v[182:185], v[222:225], v[80:83]
	v_mfma_f32_16x16x32_bf16 v[72:75], v[190:193], v[222:225], v[72:75]
	s_setprio 0
	s_barrier
	s_add_i32 s40, 0, 0x1c000
	s_add_i32 s21, s21, s43
	v_add_u32_e32 v147, s40, v155
	v_lshl_add_u64 v[138:139], v[138:139], 0, s[44:45]
	s_mov_b32 m0, s21
	ds_read_b128 v[148:151], v147
	ds_read_b128 v[226:229], v147 offset:1024
	ds_read_b128 v[230:233], v147 offset:2048
	ds_read_b128 v[234:237], v147 offset:3072
	global_load_lds_dwordx4 v[138:139], off
	v_lshl_add_u64 v[138:139], v[140:141], 0, s[44:45]
	s_add_i32 m0, s21, 0x2000
	s_nop 0
	global_load_lds_dwordx4 v[138:139], off
	s_barrier
; #define PG8_STAGE(bufoff, gbase, v0, v1) do { \
;         __builtin_amdgcn_global_load_lds((const unsigned*)((const char*)(gbase) + (v0)), (LAS unsigned*)(lds + (bufoff) + ldsw), 16, 0, 0); \
;         __builtin_amdgcn_global_load_lds((const unsigned*)((const char*)(gbase) + (v1)), (LAS unsigned*)(lds + (bufoff) + ldsw + 8192), 16, 0, 0); } while (0)
; #define PG8_LDA(dst, b, h) do { _Pragma("unroll") for (int m = 0; m < 4; ++m) _Pragma("unroll") for (int k = 0; k < 2; ++k) dst[m][k] = *(const LAS bf16x8*)(lds + PG8_SA(b, h) + aoff + m * 2048 + k * 1024); } while (0)
; #define PG8_MMA(ai, bj, At, Bt) do { __builtin_amdgcn_s_setprio(1); _Pragma("unroll") for (int m = 0; m < 4; ++m) _Pragma("unroll") for (int n = 0; n < 2; ++n) _Pragma("unroll") for (int k = 0; k < 2; ++k) \
;         acc[ai][bj][m][n] = __builtin_amdgcn_mfma_f32_16x16x32_bf16(Bt[n][k], At[m][k], acc[ai][bj][m][n], 0, 0, 0); __builtin_amdgcn_s_setprio(0); } while (0)
; #define PG8_WAIT_V(n) asm volatile("s_waitcnt vmcnt(" #n ")" ::: "memory")
; #define PG8_WAIT_L(n) asm volatile("s_waitcnt lgkmcnt(" #n ")" ::: "memory")
; #define PG8_BAR __builtin_amdgcn_s_barrier()
; #define PG8_SCHED __builtin_amdgcn_sched_barrier(0)
; template <class Epi, class Sched>
; __device__ __forceinline__ void gemm_phase(LAS unsigned char* lds, const Sched& S, const Epi& E) {
;     ...
;         for (int t = 0; t < nt; t += 2) {
;             const bool last = (t == nt - 2);
;             const char* a1 = cA + (size_t)(t + 1) * kstep;
;             const char* a2 = last ? nA : cA + (size_t)(t + 2) * kstep; const char* b2 = last ? nB : cB + (size_t)(t + 2) * kstep;
;             const char* a3 = a2 + kstep; const char* b3 = b2 + kstep;
;             const unsigned xA0 = last ? nvA0 : vA0, xA1 = last ? nvA1 : vA1, xB0 = last ? nvB0 : vB0, xB1 = last ? nvB1 : vB1;
;             const size_t xhA = last ? nhA : hA, xhB = last ? nhB : hB;
;     ...
;             PG8_BAR; PG8_WAIT_L(0); PG8_MMA(0, 1, At, B1); PG8_BAR;
;             PG8_LDA(At, 1, 1); PG8_STAGE(PG8_SA(1, 0), a3, xA0, xA1);
;             PG8_BAR; PG8_WAIT_L(0); PG8_MMA(1, 0, At, B0); PG8_BAR; PG8_SCHED;
;             PG8_STAGE(PG8_SB(1, 1), b3 + xhB, xB0, xB1);
;             PG8_WAIT_V(6); PG8_BAR; PG8_MMA(1, 1, At, B1); PG8_BAR;
	s_waitcnt lgkmcnt(0)
	s_setprio 1
	v_mfma_f32_16x16x32_bf16 v[116:119], v[148:151], v[194:197], v[116:119]
	v_mfma_f32_16x16x32_bf16 v[108:111], v[230:233], v[194:197], v[108:111]
	v_mfma_f32_16x16x32_bf16 v[100:103], v[148:151], v[202:205], v[100:103]
	v_mfma_f32_16x16x32_bf16 v[92:95], v[230:233], v[202:205], v[92:95]
	v_mfma_f32_16x16x32_bf16 v[84:87], v[148:151], v[210:213], v[84:87]
	v_mfma_f32_16x16x32_bf16 v[76:79], v[230:233], v[210:213], v[76:79]
	v_mfma_f32_16x16x32_bf16 v[68:71], v[148:151], v[218:221], v[68:71]
	v_mfma_f32_16x16x32_bf16 v[64:67], v[230:233], v[218:221], v[64:67]
	v_mfma_f32_16x16x32_bf16 v[116:119], v[226:229], v[198:201], v[116:119]
	v_mfma_f32_16x16x32_bf16 v[108:111], v[234:237], v[198:201], v[108:111]
	v_mfma_f32_16x16x32_bf16 v[100:103], v[226:229], v[206:209], v[100:103]
	v_mfma_f32_16x16x32_bf16 v[92:95], v[234:237], v[206:209], v[92:95]
	v_mfma_f32_16x16x32_bf16 v[84:87], v[226:229], v[214:217], v[84:87]
	v_mfma_f32_16x16x32_bf16 v[76:79], v[234:237], v[214:217], v[76:79]
	v_mfma_f32_16x16x32_bf16 v[68:71], v[226:229], v[222:225], v[68:71]
	v_mfma_f32_16x16x32_bf16 v[64:67], v[234:237], v[222:225], v[64:67]
	s_setprio 0
	s_mov_b32 m0, s64
	v_lshl_add_u64 v[138:139], v[242:243], 0, s[44:45]
	s_barrier
	ds_read_b128 v[194:197], v143 offset:49152
	ds_read_b128 v[198:201], v143 offset:50176
	ds_read_b128 v[202:205], v143 offset:51200
	ds_read_b128 v[206:209], v143 offset:52224
	ds_read_b128 v[210:213], v143 offset:53248
	ds_read_b128 v[214:217], v143 offset:54272
	ds_read_b128 v[218:221], v143 offset:55296
	ds_read_b128 v[222:225], v143 offset:56320
	global_load_lds_dwordx4 v[138:139], off
	v_lshl_add_u64 v[138:139], v[244:245], 0, s[44:45]
	s_mov_b32 m0, s65
	s_nop 0
	global_load_lds_dwordx4 v[138:139], off
	s_barrier
	s_waitcnt lgkmcnt(0)
	s_setprio 1
	v_mfma_f32_16x16x32_bf16 v[60:63], v[158:161], v[194:197], v[60:63]
	v_mfma_f32_16x16x32_bf16 v[56:59], v[186:189], v[194:197], v[56:59]
	v_mfma_f32_16x16x32_bf16 v[44:47], v[158:161], v[202:205], v[44:47]
	v_mfma_f32_16x16x32_bf16 v[40:43], v[186:189], v[202:205], v[40:43]
	v_mfma_f32_16x16x32_bf16 v[28:31], v[158:161], v[210:213], v[28:31]
	v_mfma_f32_16x16x32_bf16 v[24:27], v[186:189], v[210:213], v[24:27]
	v_mfma_f32_16x16x32_bf16 v[12:15], v[158:161], v[218:221], v[12:15]
	v_mfma_f32_16x16x32_bf16 v[8:11], v[186:189], v[218:221], v[8:11]
	v_mfma_f32_16x16x32_bf16 v[60:63], v[182:185], v[198:201], v[60:63]
	v_mfma_f32_16x16x32_bf16 v[56:59], v[190:193], v[198:201], v[56:59]
	v_mfma_f32_16x16x32_bf16 v[44:47], v[182:185], v[206:209], v[44:47]
	v_mfma_f32_16x16x32_bf16 v[40:43], v[190:193], v[206:209], v[40:43]
	v_mfma_f32_16x16x32_bf16 v[28:31], v[182:185], v[214:217], v[28:31]
	v_mfma_f32_16x16x32_bf16 v[24:27], v[190:193], v[214:217], v[24:27]
	v_mfma_f32_16x16x32_bf16 v[12:15], v[182:185], v[222:225], v[12:15]
	v_mfma_f32_16x16x32_bf16 v[8:11], v[190:193], v[222:225], v[8:11]
	s_setprio 0
	s_barrier
	s_add_u32 s38, s38, 0x80080
	s_addc_u32 s39, s39, 0
	s_add_i32 s21, s40, s43
	s_mov_b32 m0, s21
	s_nop 0
	global_load_lds_dwordx4 v136, s[38:39]
	s_add_i32 m0, s21, 0x2000
	s_nop 0
	global_load_lds_dwordx4 v146, s[38:39]
	s_waitcnt vmcnt(6)
	s_barrier
	s_setprio 1
	v_mfma_f32_16x16x32_bf16 v[52:55], v[148:151], v[194:197], v[52:55]
	v_mfma_f32_16x16x32_bf16 v[48:51], v[230:233], v[194:197], v[48:51]
	v_mfma_f32_16x16x32_bf16 v[36:39], v[148:151], v[202:205], v[36:39]
	v_mfma_f32_16x16x32_bf16 v[32:35], v[230:233], v[202:205], v[32:35]
	v_mfma_f32_16x16x32_bf16 v[20:23], v[148:151], v[210:213], v[20:23]
	v_mfma_f32_16x16x32_bf16 v[16:19], v[230:233], v[210:213], v[16:19]
	v_mfma_f32_16x16x32_bf16 v[4:7], v[148:151], v[218:221], v[4:7]
	v_mfma_f32_16x16x32_bf16 v[0:3], v[230:233], v[218:221], v[0:3]
	v_mfma_f32_16x16x32_bf16 v[52:55], v[226:229], v[198:201], v[52:55]
	v_mfma_f32_16x16x32_bf16 v[48:51], v[234:237], v[198:201], v[48:51]
	v_mfma_f32_16x16x32_bf16 v[36:39], v[226:229], v[206:209], v[36:39]
	v_mfma_f32_16x16x32_bf16 v[32:35], v[234:237], v[206:209], v[32:35]
	v_mfma_f32_16x16x32_bf16 v[20:23], v[226:229], v[214:217], v[20:23]
	v_mfma_f32_16x16x32_bf16 v[16:19], v[234:237], v[214:217], v[16:19]
	v_mfma_f32_16x16x32_bf16 v[4:7], v[226:229], v[222:225], v[4:7]
	v_mfma_f32_16x16x32_bf16 v[0:3], v[234:237], v[222:225], v[0:3]
	s_setprio 0
	s_add_i32 s15, s15, 2
	s_add_u32 s26, s26, 0x100
	s_addc_u32 s27, s27, 0
	s_add_u32 s34, s34, 0x100
	s_addc_u32 s35, s35, 0
	s_cmp_gt_u32 s15, 29
	s_cbranch_scc1 .Lrot_exit_3
	s_cmp_eq_u32 s15, 28
	s_cselect_b64 s[40:41], -1, 0
	s_and_b64 vcc, exec, s[40:41]
	v_mov_b64_e32 v[148:149], v[130:131]
	v_mov_b64_e32 v[150:151], v[128:129]
	v_mov_b32_e32 v146, v156
	v_mov_b32_e32 v136, v145
	s_mov_b64 s[38:39], s[24:25]
	s_cbranch_vccnz .Lrot_join_3
	v_mov_b64_e32 v[148:149], v[134:135]
	v_mov_b64_e32 v[150:151], v[132:133]
	v_mov_b32_e32 v146, v142
	v_mov_b32_e32 v136, v144
	s_mov_b64 s[38:39], s[34:35]

; #define PG8_STAGE(bufoff, gbase, v0, v1) do { \
;         __builtin_amdgcn_global_load_lds((const unsigned*)((const char*)(gbase) + (v0)), (LAS unsigned*)(lds + (bufoff) + ldsw), 16, 0, 0); \
;         __builtin_amdgcn_global_load_lds((const unsigned*)((const char*)(gbase) + (v1)), (LAS unsigned*)(lds + (bufoff) + ldsw + 8192), 16, 0, 0); } while (0)
; #define PG8_LDA(dst, b, h) do { _Pragma("unroll") for (int m = 0; m < 4; ++m) _Pragma("unroll") for (int k = 0; k < 2; ++k) dst[m][k] = *(const LAS bf16x8*)(lds + PG8_SA(b, h) + aoff + m * 2048 + k * 1024); } while (0)
; #define PG8_LDB(dst, b, h) do { _Pragma("unroll") for (int n = 0; n < 2; ++n) _Pragma("unroll") for (int k = 0; k < 2; ++k) dst[n][k] = *(const LAS bf16x8*)(lds + PG8_SB(b, h) + boff + n * 2048 + k * 1024); } while (0)
; #define PG8_MMA(ai, bj, At, Bt) do { __builtin_amdgcn_s_setprio(1); _Pragma("unroll") for (int m = 0; m < 4; ++m) _Pragma("unroll") for (int n = 0; n < 2; ++n) _Pragma("unroll") for (int k = 0; k < 2; ++k) \
;         acc[ai][bj][m][n] = __builtin_amdgcn_mfma_f32_16x16x32_bf16(Bt[n][k], At[m][k], acc[ai][bj][m][n], 0, 0, 0); __builtin_amdgcn_s_setprio(0); } while (0)
; #define PG8_WAIT_L(n) asm volatile("s_waitcnt lgkmcnt(" #n ")" ::: "memory")
; #define PG8_BAR __builtin_amdgcn_s_barrier()
; template <class Epi, class Sched>
; __device__ __forceinline__ void gemm_phase(LAS unsigned char* lds, const Sched& S, const Epi& E) {
;     ...
;             const char* a1 = cA + (size_t)(t + 1) * kstep;
;             const char* a2 = last ? nA : cA + (size_t)(t + 2) * kstep; const char* b2 = last ? nB : cB + (size_t)(t + 2) * kstep;
;             const char* a3 = a2 + kstep; const char* b3 = b2 + kstep;
;             const unsigned xA0 = last ? nvA0 : vA0, xA1 = last ? nvA1 : vA1, xB0 = last ? nvB0 : vB0, xB1 = last ? nvB1 : vB1;
;             const size_t xhA = last ? nhA : hA, xhB = last ? nhB : hB;
;             PG8_LDB(B0, 0, 0); PG8_SCHED; PG8_LDA(At, 0, 0); PG8_STAGE(PG8_SA(1, 1), a1 + hA, vA0, vA1);
;             PG8_WAIT_L(8); PG8_BAR; PG8_WAIT_L(0); PG8_MMA(0, 0, At, B0); PG8_BAR; PG8_SCHED;
;             PG8_LDB(B1, 0, 1); PG8_STAGE(PG8_SB(0, 0), b2, xB0, xB1);
;             PG8_BAR; PG8_WAIT_L(0); PG8_MMA(0, 1, At, B1); PG8_BAR;
;             PG8_LDA(At, 0, 1); PG8_STAGE(PG8_SA(0, 0), a2, xA0, xA1);
;             PG8_BAR; PG8_WAIT_L(0); PG8_MMA(1, 0, At, B0); PG8_BAR; PG8_SCHED;
.LBB0_847:
	s_add_u32 s15, s24, 0xffe00080
	s_addc_u32 s70, s25, -1
	s_and_b64 s[38:39], exec, s[38:39]
	s_cselect_b32 s39, s21, s70
	s_cselect_b32 s38, s20, s15
	s_add_i32 s15, 0, 0x10000
	v_add_u32_e32 v138, s15, v147
	ds_read_b128 v[150:153], v138
	ds_read_b128 v[154:157], v138 offset:1024
	ds_read_b128 v[158:161], v138 offset:2048
	ds_read_b128 v[182:185], v138 offset:3072
	v_lshl_add_u64 v[138:139], s[24:25], 0, v[136:137]
	s_add_i32 m0, s49, 0xc000
	ds_read_b128 v[186:189], v148
	ds_read_b128 v[190:193], v148 offset:1024
	ds_read_b128 v[194:197], v148 offset:2048
	ds_read_b128 v[198:201], v148 offset:3072
	ds_read_b128 v[202:205], v148 offset:4096
	ds_read_b128 v[206:209], v148 offset:5120
	ds_read_b128 v[210:213], v148 offset:6144
	ds_read_b128 v[214:217], v148 offset:7168
	global_load_lds_dwordx4 v[138:139], off
	v_lshl_add_u64 v[138:139], s[24:25], 0, v[132:133]
	s_add_i32 m0, s49, 0xe000
	s_nop 0
	global_load_lds_dwordx4 v[138:139], off
	s_waitcnt lgkmcnt(8)
	s_barrier
	s_waitcnt lgkmcnt(0)
	s_setprio 1
	v_mfma_f32_16x16x32_bf16 v[124:127], v[150:153], v[186:189], v[124:127]
	v_mfma_f32_16x16x32_bf16 v[120:123], v[158:161], v[186:189], v[120:123]
	v_mfma_f32_16x16x32_bf16 v[108:111], v[150:153], v[194:197], v[108:111]
	v_mfma_f32_16x16x32_bf16 v[104:107], v[158:161], v[194:197], v[104:107]
	v_mfma_f32_16x16x32_bf16 v[100:103], v[150:153], v[202:205], v[100:103]
	v_mfma_f32_16x16x32_bf16 v[96:99], v[158:161], v[202:205], v[96:99]
	v_mfma_f32_16x16x32_bf16 v[84:87], v[150:153], v[210:213], v[84:87]
	v_mfma_f32_16x16x32_bf16 v[80:83], v[158:161], v[210:213], v[80:83]
	v_mfma_f32_16x16x32_bf16 v[124:127], v[154:157], v[190:193], v[124:127]
	v_mfma_f32_16x16x32_bf16 v[120:123], v[182:185], v[190:193], v[120:123]
	v_mfma_f32_16x16x32_bf16 v[108:111], v[154:157], v[198:201], v[108:111]
	v_mfma_f32_16x16x32_bf16 v[104:107], v[182:185], v[198:201], v[104:107]
	v_mfma_f32_16x16x32_bf16 v[100:103], v[154:157], v[206:209], v[100:103]
	v_mfma_f32_16x16x32_bf16 v[96:99], v[182:185], v[206:209], v[96:99]
	v_mfma_f32_16x16x32_bf16 v[84:87], v[154:157], v[214:217], v[84:87]
	v_mfma_f32_16x16x32_bf16 v[80:83], v[182:185], v[214:217], v[80:83]
	s_setprio 0
	s_barrier
	s_add_i32 s82, 0, 0x14000
	v_add_u32_e32 v138, s82, v147
	s_add_i32 s15, s15, s48
	ds_read_b128 v[218:221], v138
	ds_read_b128 v[222:225], v138 offset:1024
	ds_read_b128 v[226:229], v138 offset:2048
	ds_read_b128 v[230:233], v138 offset:3072
	v_lshl_add_u64 v[138:139], s[34:35], 0, v[142:143]
	s_mov_b32 m0, s15
	v_lshl_add_u64 v[140:141], s[34:35], 0, v[134:135]
	global_load_lds_dwordx4 v[138:139], off
	s_add_i32 m0, s15, 0x2000
	s_nop 0
	global_load_lds_dwordx4 v[140:141], off
	s_barrier
	s_waitcnt lgkmcnt(0)
	s_setprio 1
	v_mfma_f32_16x16x32_bf16 v[116:119], v[218:221], v[186:189], v[116:119]
	v_mfma_f32_16x16x32_bf16 v[112:115], v[226:229], v[186:189], v[112:115]
	v_mfma_f32_16x16x32_bf16 v[92:95], v[218:221], v[194:197], v[92:95]
	v_mfma_f32_16x16x32_bf16 v[88:91], v[226:229], v[194:197], v[88:91]
	v_mfma_f32_16x16x32_bf16 v[76:79], v[218:221], v[202:205], v[76:79]
	v_mfma_f32_16x16x32_bf16 v[72:75], v[226:229], v[202:205], v[72:75]
	v_mfma_f32_16x16x32_bf16 v[68:71], v[218:221], v[210:213], v[68:71]
	v_mfma_f32_16x16x32_bf16 v[64:67], v[226:229], v[210:213], v[64:67]
	v_mfma_f32_16x16x32_bf16 v[116:119], v[222:225], v[190:193], v[116:119]
	v_mfma_f32_16x16x32_bf16 v[112:115], v[230:233], v[190:193], v[112:115]
	v_mfma_f32_16x16x32_bf16 v[92:95], v[222:225], v[198:201], v[92:95]
	v_mfma_f32_16x16x32_bf16 v[88:91], v[230:233], v[198:201], v[88:91]
	v_mfma_f32_16x16x32_bf16 v[76:79], v[222:225], v[206:209], v[76:79]
	v_mfma_f32_16x16x32_bf16 v[72:75], v[230:233], v[206:209], v[72:75]
	v_mfma_f32_16x16x32_bf16 v[68:71], v[222:225], v[214:217], v[68:71]
	v_mfma_f32_16x16x32_bf16 v[64:67], v[230:233], v[214:217], v[64:67]
	s_setprio 0
	s_mov_b32 m0, s49
	v_lshl_add_u64 v[234:235], s[38:39], 0, v[142:143]
	s_barrier
	ds_read_b128 v[186:189], v148 offset:16384
	ds_read_b128 v[190:193], v148 offset:17408
	ds_read_b128 v[194:197], v148 offset:18432
	ds_read_b128 v[198:201], v148 offset:19456
	ds_read_b128 v[202:205], v148 offset:20480
	ds_read_b128 v[206:209], v148 offset:21504
	ds_read_b128 v[210:213], v148 offset:22528
	ds_read_b128 v[214:217], v148 offset:23552
	global_load_lds_dwordx4 v[234:235], off
	v_lshl_add_u64 v[236:237], s[38:39], 0, v[134:135]
	s_mov_b32 m0, s50
	s_nop 0
	global_load_lds_dwordx4 v[236:237], off
	s_barrier
	s_waitcnt lgkmcnt(0)
	s_setprio 1
	v_mfma_f32_16x16x32_bf16 v[60:63], v[150:153], v[186:189], v[60:63]
	v_mfma_f32_16x16x32_bf16 v[56:59], v[158:161], v[186:189], v[56:59]
	v_mfma_f32_16x16x32_bf16 v[44:47], v[150:153], v[194:197], v[44:47]
	v_mfma_f32_16x16x32_bf16 v[40:43], v[158:161], v[194:197], v[40:43]
	v_mfma_f32_16x16x32_bf16 v[28:31], v[150:153], v[202:205], v[28:31]
	v_mfma_f32_16x16x32_bf16 v[24:27], v[158:161], v[202:205], v[24:27]
	v_mfma_f32_16x16x32_bf16 v[12:15], v[150:153], v[210:213], v[12:15]
	v_mfma_f32_16x16x32_bf16 v[8:11], v[158:161], v[210:213], v[8:11]
	v_mfma_f32_16x16x32_bf16 v[60:63], v[154:157], v[190:193], v[60:63]
	v_mfma_f32_16x16x32_bf16 v[56:59], v[182:185], v[190:193], v[56:59]
	v_mfma_f32_16x16x32_bf16 v[44:47], v[154:157], v[198:201], v[44:47]
	v_mfma_f32_16x16x32_bf16 v[40:43], v[182:185], v[198:201], v[40:43]
	v_mfma_f32_16x16x32_bf16 v[28:31], v[154:157], v[206:209], v[28:31]
	v_mfma_f32_16x16x32_bf16 v[24:27], v[182:185], v[206:209], v[24:27]
	v_mfma_f32_16x16x32_bf16 v[12:15], v[154:157], v[214:217], v[12:15]
	v_mfma_f32_16x16x32_bf16 v[8:11], v[182:185], v[214:217], v[8:11]
	s_setprio 0
	s_barrier
; #define PG8_STAGE(bufoff, gbase, v0, v1) do { \
;         __builtin_amdgcn_global_load_lds((const unsigned*)((const char*)(gbase) + (v0)), (LAS unsigned*)(lds + (bufoff) + ldsw), 16, 0, 0); \
;         __builtin_amdgcn_global_load_lds((const unsigned*)((const char*)(gbase) + (v1)), (LAS unsigned*)(lds + (bufoff) + ldsw + 8192), 16, 0, 0); } while (0)
; #define PG8_LDA(dst, b, h) do { _Pragma("unroll") for (int m = 0; m < 4; ++m) _Pragma("unroll") for (int k = 0; k < 2; ++k) dst[m][k] = *(const LAS bf16x8*)(lds + PG8_SA(b, h) + aoff + m * 2048 + k * 1024); } while (0)
; #define PG8_LDB(dst, b, h) do { _Pragma("unroll") for (int n = 0; n < 2; ++n) _Pragma("unroll") for (int k = 0; k < 2; ++k) dst[n][k] = *(const LAS bf16x8*)(lds + PG8_SB(b, h) + boff + n * 2048 + k * 1024); } while (0)
; #define PG8_MMA(ai, bj, At, Bt) do { __builtin_amdgcn_s_setprio(1); _Pragma("unroll") for (int m = 0; m < 4; ++m) _Pragma("unroll") for (int n = 0; n < 2; ++n) _Pragma("unroll") for (int k = 0; k < 2; ++k) \
;         acc[ai][bj][m][n] = __builtin_amdgcn_mfma_f32_16x16x32_bf16(Bt[n][k], At[m][k], acc[ai][bj][m][n], 0, 0, 0); __builtin_amdgcn_s_setprio(0); } while (0)
; #define PG8_WAIT_V(n) asm volatile("s_waitcnt vmcnt(" #n ")" ::: "memory")
; #define PG8_WAIT_L(n) asm volatile("s_waitcnt lgkmcnt(" #n ")" ::: "memory")
; #define PG8_BAR __builtin_amdgcn_s_barrier()
; #define PG8_SCHED __builtin_amdgcn_sched_barrier(0)
; template <class Epi, class Sched>
; __device__ __forceinline__ void gemm_phase(LAS unsigned char* lds, const Sched& S, const Epi& E) {
;     ...
;             PG8_STAGE(PG8_SB(0, 1), b2 + xhB, xB0, xB1);
;             PG8_WAIT_V(6); PG8_BAR; PG8_MMA(1, 1, At, B1); PG8_BAR;
;             PG8_LDB(B0, 1, 0); PG8_SCHED; PG8_LDA(At, 1, 0); PG8_STAGE(PG8_SA(0, 1), a2 + xhA, xA0, xA1);
;             PG8_WAIT_L(8); PG8_BAR; PG8_WAIT_L(0); PG8_MMA(0, 0, At, B0); PG8_BAR; PG8_SCHED;
;             PG8_LDB(B1, 1, 1); PG8_STAGE(PG8_SB(1, 0), b3, xB0, xB1);
	s_add_u32 s70, s34, 0x200000
	s_addc_u32 s71, s35, 0
	s_add_i32 s15, s82, s48
	v_lshl_add_u64 v[150:151], s[70:71], 0, v[142:143]
	s_mov_b32 m0, s15
	s_nop 0
	global_load_lds_dwordx4 v[150:151], off
	v_lshl_add_u64 v[150:151], s[70:71], 0, v[134:135]
	s_add_i32 m0, s15, 0x2000
	s_nop 0
	global_load_lds_dwordx4 v[150:151], off
	s_add_i32 s15, 0, 0x18000
	v_add_u32_e32 v149, s15, v147
	s_waitcnt vmcnt(6)
	s_barrier
	s_setprio 1
	v_mfma_f32_16x16x32_bf16 v[52:55], v[218:221], v[186:189], v[52:55]
	ds_read_b128 v[150:153], v149
	v_mfma_f32_16x16x32_bf16 v[48:51], v[226:229], v[186:189], v[48:51]
	ds_read_b128 v[154:157], v149 offset:1024
	v_mfma_f32_16x16x32_bf16 v[36:39], v[218:221], v[194:197], v[36:39]
	ds_read_b128 v[158:161], v149 offset:2048
	v_mfma_f32_16x16x32_bf16 v[32:35], v[226:229], v[194:197], v[32:35]
	ds_read_b128 v[182:185], v149 offset:3072
	v_mfma_f32_16x16x32_bf16 v[20:23], v[218:221], v[202:205], v[20:23]
	v_mfma_f32_16x16x32_bf16 v[16:19], v[226:229], v[202:205], v[16:19]
	v_mfma_f32_16x16x32_bf16 v[4:7], v[218:221], v[210:213], v[4:7]
	v_mfma_f32_16x16x32_bf16 v[0:3], v[226:229], v[210:213], v[0:3]
	v_mfma_f32_16x16x32_bf16 v[52:55], v[222:225], v[190:193], v[52:55]
	v_mfma_f32_16x16x32_bf16 v[48:51], v[230:233], v[190:193], v[48:51]
	v_mfma_f32_16x16x32_bf16 v[36:39], v[222:225], v[198:201], v[36:39]
	v_mfma_f32_16x16x32_bf16 v[32:35], v[230:233], v[198:201], v[32:35]
	v_mfma_f32_16x16x32_bf16 v[20:23], v[222:225], v[206:209], v[20:23]
	v_mfma_f32_16x16x32_bf16 v[16:19], v[230:233], v[206:209], v[16:19]
	v_mfma_f32_16x16x32_bf16 v[4:7], v[222:225], v[214:217], v[4:7]
	v_mfma_f32_16x16x32_bf16 v[0:3], v[230:233], v[214:217], v[0:3]
	s_setprio 0
	s_barrier
	s_add_u32 s38, s38, 0x200000
	s_addc_u32 s39, s39, 0
	s_mov_b32 m0, s51
	v_lshl_add_u64 v[218:219], s[38:39], 0, v[142:143]
	ds_read_b128 v[186:189], v148 offset:32768
	ds_read_b128 v[190:193], v148 offset:33792
	ds_read_b128 v[194:197], v148 offset:34816
	ds_read_b128 v[198:201], v148 offset:35840
	ds_read_b128 v[202:205], v148 offset:36864
	ds_read_b128 v[206:209], v148 offset:37888
	ds_read_b128 v[210:213], v148 offset:38912
	ds_read_b128 v[214:217], v148 offset:39936
	global_load_lds_dwordx4 v[218:219], off
	v_lshl_add_u64 v[218:219], s[38:39], 0, v[134:135]
	s_mov_b32 m0, s54
	s_nop 0
	global_load_lds_dwordx4 v[218:219], off
	s_waitcnt lgkmcnt(8)
	s_barrier
	s_waitcnt lgkmcnt(0)
	s_setprio 1
	v_mfma_f32_16x16x32_bf16 v[124:127], v[150:153], v[186:189], v[124:127]
	v_mfma_f32_16x16x32_bf16 v[120:123], v[158:161], v[186:189], v[120:123]
	v_mfma_f32_16x16x32_bf16 v[108:111], v[150:153], v[194:197], v[108:111]
	v_mfma_f32_16x16x32_bf16 v[104:107], v[158:161], v[194:197], v[104:107]
	v_mfma_f32_16x16x32_bf16 v[100:103], v[150:153], v[202:205], v[100:103]
	v_mfma_f32_16x16x32_bf16 v[96:99], v[158:161], v[202:205], v[96:99]
	v_mfma_f32_16x16x32_bf16 v[84:87], v[150:153], v[210:213], v[84:87]
	v_mfma_f32_16x16x32_bf16 v[80:83], v[158:161], v[210:213], v[80:83]
	v_mfma_f32_16x16x32_bf16 v[124:127], v[154:157], v[190:193], v[124:127]
	v_mfma_f32_16x16x32_bf16 v[120:123], v[182:185], v[190:193], v[120:123]
	v_mfma_f32_16x16x32_bf16 v[108:111], v[154:157], v[198:201], v[108:111]
	v_mfma_f32_16x16x32_bf16 v[104:107], v[182:185], v[198:201], v[104:107]
	v_mfma_f32_16x16x32_bf16 v[100:103], v[154:157], v[206:209], v[100:103]
	v_mfma_f32_16x16x32_bf16 v[96:99], v[182:185], v[206:209], v[96:99]
	v_mfma_f32_16x16x32_bf16 v[84:87], v[154:157], v[214:217], v[84:87]
	v_mfma_f32_16x16x32_bf16 v[80:83], v[182:185], v[214:217], v[80:83]
	s_setprio 0
	s_barrier
	s_add_i32 s38, 0, 0x1c000
	s_add_i32 s15, s15, s48
	v_add_u32_e32 v149, s38, v147
	v_lshl_add_u64 v[138:139], v[138:139], 0, s[44:45]
	s_mov_b32 m0, s15
	ds_read_b128 v[218:221], v149
	ds_read_b128 v[222:225], v149 offset:1024
	ds_read_b128 v[226:229], v149 offset:2048
	ds_read_b128 v[230:233], v149 offset:3072
	global_load_lds_dwordx4 v[138:139], off
	v_lshl_add_u64 v[138:139], v[140:141], 0, s[44:45]
	s_add_i32 m0, s15, 0x2000
	s_nop 0
	global_load_lds_dwordx4 v[138:139], off
	s_barrier
; #define PG8_STAGE(bufoff, gbase, v0, v1) do { \
;         __builtin_amdgcn_global_load_lds((const unsigned*)((const char*)(gbase) + (v0)), (LAS unsigned*)(lds + (bufoff) + ldsw), 16, 0, 0); \
;         __builtin_amdgcn_global_load_lds((const unsigned*)((const char*)(gbase) + (v1)), (LAS unsigned*)(lds + (bufoff) + ldsw + 8192), 16, 0, 0); } while (0)
; #define PG8_LDA(dst, b, h) do { _Pragma("unroll") for (int m = 0; m < 4; ++m) _Pragma("unroll") for (int k = 0; k < 2; ++k) dst[m][k] = *(const LAS bf16x8*)(lds + PG8_SA(b, h) + aoff + m * 2048 + k * 1024); } while (0)
; #define PG8_MMA(ai, bj, At, Bt) do { __builtin_amdgcn_s_setprio(1); _Pragma("unroll") for (int m = 0; m < 4; ++m) _Pragma("unroll") for (int n = 0; n < 2; ++n) _Pragma("unroll") for (int k = 0; k < 2; ++k) \
;         acc[ai][bj][m][n] = __builtin_amdgcn_mfma_f32_16x16x32_bf16(Bt[n][k], At[m][k], acc[ai][bj][m][n], 0, 0, 0); __builtin_amdgcn_s_setprio(0); } while (0)
; #define PG8_WAIT_V(n) asm volatile("s_waitcnt vmcnt(" #n ")" ::: "memory")
; #define PG8_WAIT_L(n) asm volatile("s_waitcnt lgkmcnt(" #n ")" ::: "memory")
; #define PG8_BAR __builtin_amdgcn_s_barrier()
; #define PG8_SCHED __builtin_amdgcn_sched_barrier(0)
; template <class Epi, class Sched>
; __device__ __forceinline__ void gemm_phase(LAS unsigned char* lds, const Sched& S, const Epi& E) {
;     ...
;         for (int t = 0; t < nt; t += 2) {
;             const bool last = (t == nt - 2);
;             const char* a1 = cA + (size_t)(t + 1) * kstep;
;             const char* a2 = last ? nA : cA + (size_t)(t + 2) * kstep; const char* b2 = last ? nB : cB + (size_t)(t + 2) * kstep;
;             const char* a3 = a2 + kstep; const char* b3 = b2 + kstep;
;             const unsigned xA0 = last ? nvA0 : vA0, xA1 = last ? nvA1 : vA1, xB0 = last ? nvB0 : vB0, xB1 = last ? nvB1 : vB1;
;             const size_t xhA = last ? nhA : hA, xhB = last ? nhB : hB;
;     ...
;             PG8_BAR; PG8_WAIT_L(0); PG8_MMA(0, 1, At, B1); PG8_BAR;
;             PG8_LDA(At, 1, 1); PG8_STAGE(PG8_SA(1, 0), a3, xA0, xA1);
;             PG8_BAR; PG8_WAIT_L(0); PG8_MMA(1, 0, At, B0); PG8_BAR; PG8_SCHED;
;             PG8_STAGE(PG8_SB(1, 1), b3 + xhB, xB0, xB1);
;             PG8_WAIT_V(6); PG8_BAR; PG8_MMA(1, 1, At, B1); PG8_BAR;
	s_waitcnt lgkmcnt(0)
	s_setprio 1
	v_mfma_f32_16x16x32_bf16 v[116:119], v[218:221], v[186:189], v[116:119]
	v_mfma_f32_16x16x32_bf16 v[112:115], v[226:229], v[186:189], v[112:115]
	v_mfma_f32_16x16x32_bf16 v[92:95], v[218:221], v[194:197], v[92:95]
	v_mfma_f32_16x16x32_bf16 v[88:91], v[226:229], v[194:197], v[88:91]
	v_mfma_f32_16x16x32_bf16 v[76:79], v[218:221], v[202:205], v[76:79]
	v_mfma_f32_16x16x32_bf16 v[72:75], v[226:229], v[202:205], v[72:75]
	v_mfma_f32_16x16x32_bf16 v[68:71], v[218:221], v[210:213], v[68:71]
	v_mfma_f32_16x16x32_bf16 v[64:67], v[226:229], v[210:213], v[64:67]
	v_mfma_f32_16x16x32_bf16 v[116:119], v[222:225], v[190:193], v[116:119]
	v_mfma_f32_16x16x32_bf16 v[112:115], v[230:233], v[190:193], v[112:115]
	v_mfma_f32_16x16x32_bf16 v[92:95], v[222:225], v[198:201], v[92:95]
	v_mfma_f32_16x16x32_bf16 v[88:91], v[230:233], v[198:201], v[88:91]
	v_mfma_f32_16x16x32_bf16 v[76:79], v[222:225], v[206:209], v[76:79]
	v_mfma_f32_16x16x32_bf16 v[72:75], v[230:233], v[206:209], v[72:75]
	v_mfma_f32_16x16x32_bf16 v[68:71], v[222:225], v[214:217], v[68:71]
	v_mfma_f32_16x16x32_bf16 v[64:67], v[230:233], v[214:217], v[64:67]
	s_setprio 0
	s_mov_b32 m0, s65
	v_lshl_add_u64 v[138:139], v[234:235], 0, s[44:45]
	s_barrier
	ds_read_b128 v[186:189], v148 offset:49152
	ds_read_b128 v[190:193], v148 offset:50176
	ds_read_b128 v[194:197], v148 offset:51200
	ds_read_b128 v[198:201], v148 offset:52224
	ds_read_b128 v[202:205], v148 offset:53248
	ds_read_b128 v[206:209], v148 offset:54272
	ds_read_b128 v[210:213], v148 offset:55296
	ds_read_b128 v[214:217], v148 offset:56320
	global_load_lds_dwordx4 v[138:139], off
	v_lshl_add_u64 v[138:139], v[236:237], 0, s[44:45]
	s_mov_b32 m0, s66
	s_nop 0
	global_load_lds_dwordx4 v[138:139], off
	s_barrier
	s_waitcnt lgkmcnt(0)
	s_setprio 1
	v_mfma_f32_16x16x32_bf16 v[60:63], v[150:153], v[186:189], v[60:63]
	v_mfma_f32_16x16x32_bf16 v[56:59], v[158:161], v[186:189], v[56:59]
	v_mfma_f32_16x16x32_bf16 v[44:47], v[150:153], v[194:197], v[44:47]
	v_mfma_f32_16x16x32_bf16 v[40:43], v[158:161], v[194:197], v[40:43]
	v_mfma_f32_16x16x32_bf16 v[28:31], v[150:153], v[202:205], v[28:31]
	v_mfma_f32_16x16x32_bf16 v[24:27], v[158:161], v[202:205], v[24:27]
	v_mfma_f32_16x16x32_bf16 v[12:15], v[150:153], v[210:213], v[12:15]
	v_mfma_f32_16x16x32_bf16 v[8:11], v[158:161], v[210:213], v[8:11]
	v_mfma_f32_16x16x32_bf16 v[60:63], v[154:157], v[190:193], v[60:63]
	v_mfma_f32_16x16x32_bf16 v[56:59], v[182:185], v[190:193], v[56:59]
	v_mfma_f32_16x16x32_bf16 v[44:47], v[154:157], v[198:201], v[44:47]
	v_mfma_f32_16x16x32_bf16 v[40:43], v[182:185], v[198:201], v[40:43]
	v_mfma_f32_16x16x32_bf16 v[28:31], v[154:157], v[206:209], v[28:31]
	v_mfma_f32_16x16x32_bf16 v[24:27], v[182:185], v[206:209], v[24:27]
	v_mfma_f32_16x16x32_bf16 v[12:15], v[154:157], v[214:217], v[12:15]
	v_mfma_f32_16x16x32_bf16 v[8:11], v[182:185], v[214:217], v[8:11]
	s_setprio 0
	s_barrier
	s_add_u32 s34, s34, 0x200080
	s_addc_u32 s35, s35, 0
	s_add_i32 s15, s38, s48
	v_lshl_add_u64 v[138:139], s[34:35], 0, v[142:143]
	s_mov_b32 m0, s15
	v_lshl_add_u64 v[134:135], s[34:35], 0, v[134:135]
	global_load_lds_dwordx4 v[138:139], off
	s_add_i32 m0, s15, 0x2000
	s_nop 0
	global_load_lds_dwordx4 v[134:135], off
	s_waitcnt vmcnt(6)
	s_barrier
	s_setprio 1
	v_mfma_f32_16x16x32_bf16 v[52:55], v[218:221], v[186:189], v[52:55]
	v_mfma_f32_16x16x32_bf16 v[48:51], v[226:229], v[186:189], v[48:51]
	v_mfma_f32_16x16x32_bf16 v[36:39], v[218:221], v[194:197], v[36:39]
	v_mfma_f32_16x16x32_bf16 v[32:35], v[226:229], v[194:197], v[32:35]
	v_mfma_f32_16x16x32_bf16 v[20:23], v[218:221], v[202:205], v[20:23]
	v_mfma_f32_16x16x32_bf16 v[16:19], v[226:229], v[202:205], v[16:19]
	v_mfma_f32_16x16x32_bf16 v[4:7], v[218:221], v[210:213], v[4:7]
	v_mfma_f32_16x16x32_bf16 v[0:3], v[226:229], v[210:213], v[0:3]
	v_mfma_f32_16x16x32_bf16 v[52:55], v[222:225], v[190:193], v[52:55]
	v_mfma_f32_16x16x32_bf16 v[48:51], v[230:233], v[190:193], v[48:51]
	v_mfma_f32_16x16x32_bf16 v[36:39], v[222:225], v[198:201], v[36:39]
	v_mfma_f32_16x16x32_bf16 v[32:35], v[230:233], v[198:201], v[32:35]
	v_mfma_f32_16x16x32_bf16 v[20:23], v[222:225], v[206:209], v[20:23]
	v_mfma_f32_16x16x32_bf16 v[16:19], v[230:233], v[206:209], v[16:19]
	v_mfma_f32_16x16x32_bf16 v[4:7], v[222:225], v[214:217], v[4:7]
	v_mfma_f32_16x16x32_bf16 v[0:3], v[230:233], v[214:217], v[0:3]
	s_setprio 0
	s_add_i32 s11, s11, 2
	s_add_u32 s24, s24, 0x100
	s_addc_u32 s25, s25, 0
	s_add_u32 s26, s26, 0x100
	s_addc_u32 s27, s27, 0
	s_cmpk_gt_u32 s11, 0x7d
	s_cbranch_scc1 .Lrot_exit_4
	s_cmpk_eq_i32 s11, 0x7c
	s_cselect_b64 s[38:39], -1, 0
	s_and_b64 vcc, exec, s[38:39]
	v_mov_b64_e32 v[134:135], v[130:131]
	v_mov_b64_e32 v[142:143], v[128:129]
	s_mov_b64 s[34:35], s[22:23]
	s_cbranch_vccnz .Lrot_join_4
	v_mov_b64_e32 v[134:135], v[132:133]
	v_mov_b64_e32 v[142:143], v[136:137]
	s_mov_b64 s[34:35], s[26:27]
